# phase 12: bias-read batching also in the phase-12 neighbourhood-attention copies; attention workgroups start ~2.8us later so the S5 chain's first tile loads are not queued behind their staging burst
# baseline (speedup 1.0000x reference)
.LBB0_924:
	s_cmpk_lt_i32 s2, 0x60
	s_cbranch_scc1 .Lslp12_skip
	s_sleep 100

.LBB0_949:
	s_or_b64 exec, exec, s[0:1]
	v_mov_b32_e32 v66, 0xf149f2ca
	v_mov_b32_e32 v67, 0xf149f2ca
	ds_read_b32 v176, v72 offset:496
	ds_read_b32 v177, v90 offset:496
	ds_read_b32 v178, v91 offset:496
	ds_read_b32 v179, v92 offset:496
	ds_read_b32 v180, v94 offset:496
	ds_read_b32 v181, v95 offset:496
	ds_read_b32 v182, v96 offset:496
	ds_read_b32 v183, v97 offset:496
	s_waitcnt lgkmcnt(0)
	s_and_saveexec_b64 s[0:1], vcc
	s_cbranch_execz .LBB0_951
	v_mov_b32_e32 v99, v176
	v_mov_b32_e32 v98, v60
	s_waitcnt lgkmcnt(0)
	v_pk_mul_f32 v[98:99], v[98:99], s[70:71]
	s_nop 0
	v_add_f32_e32 v67, v98, v99
.LBB0_951:
	s_or_b64 exec, exec, s[0:1]
	s_and_saveexec_b64 s[0:1], s[4:5]
	s_cbranch_execz .LBB0_953
	v_mov_b32_e32 v99, v177
	v_mov_b32_e32 v98, v61
	s_waitcnt lgkmcnt(0)
	v_pk_mul_f32 v[60:61], v[98:99], s[70:71]
	s_nop 0
	v_add_f32_e32 v66, v60, v61
.LBB0_953:
	s_or_b64 exec, exec, s[0:1]
	v_mov_b32_e32 v60, 0xf149f2ca
	v_mov_b32_e32 v61, 0xf149f2ca
	s_and_saveexec_b64 s[0:1], s[6:7]
	s_cbranch_execz .LBB0_955
	v_mov_b32_e32 v99, v178
	v_mov_b32_e32 v98, v62
	s_waitcnt lgkmcnt(0)
	v_pk_mul_f32 v[98:99], v[98:99], s[70:71]
	s_nop 0
	v_add_f32_e32 v61, v98, v99
.LBB0_955:
	s_or_b64 exec, exec, s[0:1]
	s_and_saveexec_b64 s[0:1], s[8:9]
	s_cbranch_execz .LBB0_957
	v_mov_b32_e32 v99, v179
	v_mov_b32_e32 v98, v63
	s_waitcnt lgkmcnt(0)
	v_pk_mul_f32 v[62:63], v[98:99], s[70:71]
	s_nop 0
	v_add_f32_e32 v60, v62, v63
.LBB0_957:
	s_or_b64 exec, exec, s[0:1]
	v_mov_b32_e32 v62, 0xf149f2ca
	v_mov_b32_e32 v63, 0xf149f2ca
	s_and_saveexec_b64 s[0:1], s[10:11]
	s_cbranch_execz .LBB0_959
	v_mov_b32_e32 v99, v180
	v_mov_b32_e32 v98, v56
	s_waitcnt lgkmcnt(0)
	v_pk_mul_f32 v[98:99], v[98:99], s[70:71]
	s_nop 0
	v_add_f32_e32 v63, v98, v99
.LBB0_959:
	s_or_b64 exec, exec, s[0:1]
	s_and_saveexec_b64 s[0:1], s[12:13]
	s_cbranch_execz .LBB0_961
	v_mov_b32_e32 v99, v181
	v_mov_b32_e32 v98, v57
	s_waitcnt lgkmcnt(0)
	v_pk_mul_f32 v[56:57], v[98:99], s[70:71]
	s_nop 0
	v_add_f32_e32 v62, v56, v57
.LBB0_961:
	s_or_b64 exec, exec, s[0:1]
	v_mov_b32_e32 v57, 0xf149f2ca
	v_mov_b32_e32 v93, 0xf149f2ca
	s_and_saveexec_b64 s[0:1], s[14:15]
	s_cbranch_execz .LBB0_963
	v_mov_b32_e32 v99, v182
	v_mov_b32_e32 v98, v58
	s_waitcnt lgkmcnt(0)
	v_pk_mul_f32 v[98:99], v[98:99], s[70:71]
	s_nop 0
	v_add_f32_e32 v93, v98, v99
.LBB0_963:
	s_or_b64 exec, exec, s[0:1]
	s_and_saveexec_b64 s[0:1], s[16:17]
	s_cbranch_execz .LBB0_965
	v_mov_b32_e32 v57, v183
	v_mov_b32_e32 v56, v59
	s_waitcnt lgkmcnt(0)
	v_pk_mul_f32 v[56:57], v[56:57], s[70:71]
	s_nop 0
	v_add_f32_e32 v57, v56, v57
.LBB0_965:
	s_or_b64 exec, exec, s[0:1]
	v_mov_b32_e32 v56, 0xf149f2ca
	v_mov_b32_e32 v58, 0xf149f2ca
	ds_read_b32 v176, v72 offset:620
	ds_read_b32 v177, v90 offset:620
	ds_read_b32 v178, v91 offset:620
	ds_read_b32 v179, v92 offset:620
	ds_read_b32 v180, v94 offset:620
	ds_read_b32 v181, v95 offset:620
	ds_read_b32 v182, v96 offset:620
	ds_read_b32 v183, v97 offset:620
	s_waitcnt lgkmcnt(0)
	s_and_saveexec_b64 s[0:1], vcc
	s_cbranch_execz .LBB0_967
	v_mov_b32_e32 v59, v176
	v_mov_b32_e32 v58, v52
	s_waitcnt lgkmcnt(0)
	v_pk_mul_f32 v[58:59], v[58:59], s[70:71]
	s_nop 0
	v_add_f32_e32 v58, v58, v59
.LBB0_967:
	s_or_b64 exec, exec, s[0:1]
	s_and_saveexec_b64 s[0:1], s[4:5]
	s_cbranch_execz .LBB0_969
	v_mov_b32_e32 v99, v177
	v_mov_b32_e32 v98, v53
	s_waitcnt lgkmcnt(0)
	v_pk_mul_f32 v[52:53], v[98:99], s[70:71]
	s_nop 0
	v_add_f32_e32 v56, v52, v53
.LBB0_969:
	s_or_b64 exec, exec, s[0:1]
	v_mov_b32_e32 v52, 0xf149f2ca
	v_mov_b32_e32 v53, 0xf149f2ca
	s_and_saveexec_b64 s[0:1], s[6:7]
	s_cbranch_execz .LBB0_971
	v_mov_b32_e32 v99, v178
	v_mov_b32_e32 v98, v54
	s_waitcnt lgkmcnt(0)
	v_pk_mul_f32 v[98:99], v[98:99], s[70:71]
	s_nop 0
	v_add_f32_e32 v53, v98, v99
.LBB0_971:
	s_or_b64 exec, exec, s[0:1]
	s_and_saveexec_b64 s[0:1], s[8:9]
	s_cbranch_execz .LBB0_973
	v_mov_b32_e32 v99, v179
	v_mov_b32_e32 v98, v55
	s_waitcnt lgkmcnt(0)
	v_pk_mul_f32 v[54:55], v[98:99], s[70:71]
	s_nop 0
	v_add_f32_e32 v52, v54, v55
.LBB0_973:
	s_or_b64 exec, exec, s[0:1]
	v_mov_b32_e32 v54, 0xf149f2ca
	v_mov_b32_e32 v55, 0xf149f2ca
	s_and_saveexec_b64 s[0:1], s[10:11]
	s_cbranch_execz .LBB0_975
	v_mov_b32_e32 v99, v180
	v_mov_b32_e32 v98, v48
	s_waitcnt lgkmcnt(0)
	v_pk_mul_f32 v[98:99], v[98:99], s[70:71]
	s_nop 0
	v_add_f32_e32 v55, v98, v99
.LBB0_975:
	s_or_b64 exec, exec, s[0:1]
	s_and_saveexec_b64 s[0:1], s[12:13]
	s_cbranch_execz .LBB0_977
	v_mov_b32_e32 v99, v181
	v_mov_b32_e32 v98, v49
	s_waitcnt lgkmcnt(0)
	v_pk_mul_f32 v[48:49], v[98:99], s[70:71]
	s_nop 0
	v_add_f32_e32 v54, v48, v49
.LBB0_977:
	s_or_b64 exec, exec, s[0:1]
	v_mov_b32_e32 v49, 0xf149f2ca
	v_mov_b32_e32 v59, 0xf149f2ca
	s_and_saveexec_b64 s[0:1], s[14:15]
	s_cbranch_execz .LBB0_979
	v_mov_b32_e32 v99, v182
	v_mov_b32_e32 v98, v50
	s_waitcnt lgkmcnt(0)
	v_pk_mul_f32 v[98:99], v[98:99], s[70:71]
	s_nop 0
	v_add_f32_e32 v59, v98, v99
.LBB0_979:
	s_or_b64 exec, exec, s[0:1]
	s_and_saveexec_b64 s[0:1], s[16:17]
	s_cbranch_execz .LBB0_981
	v_mov_b32_e32 v49, v183
	v_mov_b32_e32 v48, v51
	s_waitcnt lgkmcnt(0)
	v_pk_mul_f32 v[48:49], v[48:49], s[70:71]
	s_nop 0
	v_add_f32_e32 v49, v48, v49
.LBB0_981:
	s_or_b64 exec, exec, s[0:1]
	v_mov_b32_e32 v48, 0xf149f2ca
	v_mov_b32_e32 v50, 0xf149f2ca
	ds_read_b32 v176, v72 offset:744
	ds_read_b32 v177, v90 offset:744
	ds_read_b32 v178, v91 offset:744
	ds_read_b32 v179, v92 offset:744
	ds_read_b32 v180, v94 offset:744
	ds_read_b32 v181, v95 offset:744
	ds_read_b32 v182, v96 offset:744
	ds_read_b32 v183, v97 offset:744
	s_waitcnt lgkmcnt(0)
	s_and_saveexec_b64 s[0:1], vcc
	s_cbranch_execz .LBB0_983
	v_mov_b32_e32 v51, v176
	v_mov_b32_e32 v50, v44
	s_waitcnt lgkmcnt(0)
	v_pk_mul_f32 v[50:51], v[50:51], s[70:71]
	s_nop 0
	v_add_f32_e32 v50, v50, v51
.LBB0_983:
	s_or_b64 exec, exec, s[0:1]
	s_and_saveexec_b64 s[0:1], s[4:5]
	s_cbranch_execz .LBB0_985
	v_mov_b32_e32 v99, v177
	v_mov_b32_e32 v98, v45
	s_waitcnt lgkmcnt(0)
	v_pk_mul_f32 v[44:45], v[98:99], s[70:71]
	s_nop 0
	v_add_f32_e32 v48, v44, v45
.LBB0_985:
	s_or_b64 exec, exec, s[0:1]
	v_mov_b32_e32 v44, 0xf149f2ca
	v_mov_b32_e32 v45, 0xf149f2ca
	s_and_saveexec_b64 s[0:1], s[6:7]
	s_cbranch_execz .LBB0_987
	v_mov_b32_e32 v99, v178
	v_mov_b32_e32 v98, v46
	s_waitcnt lgkmcnt(0)
	v_pk_mul_f32 v[98:99], v[98:99], s[70:71]
	s_nop 0
	v_add_f32_e32 v45, v98, v99
.LBB0_987:
	s_or_b64 exec, exec, s[0:1]
	s_and_saveexec_b64 s[0:1], s[8:9]
	s_cbranch_execz .LBB0_989
	v_mov_b32_e32 v99, v179
	v_mov_b32_e32 v98, v47
	s_waitcnt lgkmcnt(0)
	v_pk_mul_f32 v[46:47], v[98:99], s[70:71]
	s_nop 0
	v_add_f32_e32 v44, v46, v47
.LBB0_989:
	s_or_b64 exec, exec, s[0:1]
	v_mov_b32_e32 v46, 0xf149f2ca
	v_mov_b32_e32 v47, 0xf149f2ca
	s_and_saveexec_b64 s[0:1], s[10:11]
	s_cbranch_execz .LBB0_991
	v_mov_b32_e32 v99, v180
	v_mov_b32_e32 v98, v40
	s_waitcnt lgkmcnt(0)
	v_pk_mul_f32 v[98:99], v[98:99], s[70:71]
	s_nop 0
	v_add_f32_e32 v47, v98, v99
.LBB0_991:
	s_or_b64 exec, exec, s[0:1]
	s_and_saveexec_b64 s[0:1], s[12:13]
	s_cbranch_execz .LBB0_993
	v_mov_b32_e32 v99, v181
	v_mov_b32_e32 v98, v41
	s_waitcnt lgkmcnt(0)
	v_pk_mul_f32 v[40:41], v[98:99], s[70:71]
	s_nop 0
	v_add_f32_e32 v46, v40, v41
.LBB0_993:
	s_or_b64 exec, exec, s[0:1]
	v_mov_b32_e32 v41, 0xf149f2ca
	v_mov_b32_e32 v51, 0xf149f2ca
	s_and_saveexec_b64 s[0:1], s[14:15]
	s_cbranch_execz .LBB0_995
	v_mov_b32_e32 v99, v182
	v_mov_b32_e32 v98, v42
	s_waitcnt lgkmcnt(0)
	v_pk_mul_f32 v[98:99], v[98:99], s[70:71]
	s_nop 0
	v_add_f32_e32 v51, v98, v99
.LBB0_995:
	s_or_b64 exec, exec, s[0:1]
	s_and_saveexec_b64 s[0:1], s[16:17]
	s_cbranch_execz .LBB0_997
	v_mov_b32_e32 v41, v183
	v_mov_b32_e32 v40, v43
	s_waitcnt lgkmcnt(0)
	v_pk_mul_f32 v[40:41], v[40:41], s[70:71]
	s_nop 0
	v_add_f32_e32 v41, v40, v41
.LBB0_997:
	s_or_b64 exec, exec, s[0:1]
	v_mov_b32_e32 v40, 0xf149f2ca
	v_mov_b32_e32 v42, 0xf149f2ca
	ds_read_b32 v176, v72 offset:868
	ds_read_b32 v177, v90 offset:868
	ds_read_b32 v178, v91 offset:868
	ds_read_b32 v179, v92 offset:868
	ds_read_b32 v180, v94 offset:868
	ds_read_b32 v181, v95 offset:868
	ds_read_b32 v182, v96 offset:868
	ds_read_b32 v183, v97 offset:868
	s_waitcnt lgkmcnt(0)
	s_and_saveexec_b64 s[0:1], vcc
	s_cbranch_execz .LBB0_999
	v_mov_b32_e32 v43, v176
	v_mov_b32_e32 v42, v36
	s_waitcnt lgkmcnt(0)
	v_pk_mul_f32 v[42:43], v[42:43], s[70:71]
	s_nop 0
	v_add_f32_e32 v42, v42, v43
.LBB0_999:
	s_or_b64 exec, exec, s[0:1]
	s_and_saveexec_b64 s[0:1], s[4:5]
	s_cbranch_execz .LBB0_1001
	v_mov_b32_e32 v99, v177
	v_mov_b32_e32 v98, v37
	s_waitcnt lgkmcnt(0)
	v_pk_mul_f32 v[36:37], v[98:99], s[70:71]
	s_nop 0
	v_add_f32_e32 v40, v36, v37
.LBB0_1001:
	s_or_b64 exec, exec, s[0:1]
	v_mov_b32_e32 v36, 0xf149f2ca
	v_mov_b32_e32 v37, 0xf149f2ca
	s_and_saveexec_b64 s[0:1], s[6:7]
	s_cbranch_execz .LBB0_1003
	v_mov_b32_e32 v99, v178
	v_mov_b32_e32 v98, v38
	s_waitcnt lgkmcnt(0)
	v_pk_mul_f32 v[98:99], v[98:99], s[70:71]
	s_nop 0
	v_add_f32_e32 v37, v98, v99
.LBB0_1003:
	s_or_b64 exec, exec, s[0:1]
	s_and_saveexec_b64 s[0:1], s[8:9]
	s_cbranch_execz .LBB0_1005
	v_mov_b32_e32 v99, v179
	v_mov_b32_e32 v98, v39
	s_waitcnt lgkmcnt(0)
	v_pk_mul_f32 v[38:39], v[98:99], s[70:71]
	s_nop 0
	v_add_f32_e32 v36, v38, v39
.LBB0_1005:
	s_or_b64 exec, exec, s[0:1]
	v_mov_b32_e32 v38, 0xf149f2ca
	v_mov_b32_e32 v39, 0xf149f2ca
	s_and_saveexec_b64 s[0:1], s[10:11]
	s_cbranch_execz .LBB0_1007
	v_mov_b32_e32 v99, v180
	v_mov_b32_e32 v98, v32
	s_waitcnt lgkmcnt(0)
	v_pk_mul_f32 v[98:99], v[98:99], s[70:71]
	s_nop 0
	v_add_f32_e32 v39, v98, v99
.LBB0_1007:
	s_or_b64 exec, exec, s[0:1]
	s_and_saveexec_b64 s[0:1], s[12:13]
	s_cbranch_execz .LBB0_1009
	v_mov_b32_e32 v99, v181
	v_mov_b32_e32 v98, v33
	s_waitcnt lgkmcnt(0)
	v_pk_mul_f32 v[32:33], v[98:99], s[70:71]
	s_nop 0
	v_add_f32_e32 v38, v32, v33
.LBB0_1009:
	s_or_b64 exec, exec, s[0:1]
	v_mov_b32_e32 v33, 0xf149f2ca
	v_mov_b32_e32 v43, 0xf149f2ca
	s_and_saveexec_b64 s[0:1], s[14:15]
	s_cbranch_execz .LBB0_1011
	v_mov_b32_e32 v99, v182
	v_mov_b32_e32 v98, v34
	s_waitcnt lgkmcnt(0)
	v_pk_mul_f32 v[98:99], v[98:99], s[70:71]
	s_nop 0
	v_add_f32_e32 v43, v98, v99
.LBB0_1011:
	s_or_b64 exec, exec, s[0:1]
	s_and_saveexec_b64 s[0:1], s[16:17]
	s_cbranch_execz .LBB0_1013
	v_mov_b32_e32 v33, v183
	v_mov_b32_e32 v32, v35
	s_waitcnt lgkmcnt(0)
	v_pk_mul_f32 v[32:33], v[32:33], s[70:71]
	s_nop 0
	v_add_f32_e32 v33, v32, v33
.LBB0_1013:
	s_or_b64 exec, exec, s[0:1]
	v_mov_b32_e32 v32, 0xf149f2ca
	v_mov_b32_e32 v34, 0xf149f2ca
	ds_read_b32 v176, v72 offset:992
	ds_read_b32 v177, v90 offset:992
	ds_read_b32 v178, v91 offset:992
	ds_read_b32 v179, v92 offset:992
	ds_read_b32 v180, v94 offset:992
	ds_read_b32 v181, v95 offset:992
	ds_read_b32 v182, v96 offset:992
	ds_read_b32 v183, v97 offset:992
	s_waitcnt lgkmcnt(0)
	s_and_saveexec_b64 s[0:1], vcc
	s_cbranch_execz .LBB0_1015
	v_mov_b32_e32 v35, v176
	v_mov_b32_e32 v34, v28
	s_waitcnt lgkmcnt(0)
	v_pk_mul_f32 v[34:35], v[34:35], s[70:71]
	s_nop 0
	v_add_f32_e32 v34, v34, v35
.LBB0_1015:
	s_or_b64 exec, exec, s[0:1]
	s_and_saveexec_b64 s[0:1], s[4:5]
	s_cbranch_execz .LBB0_1017
	v_mov_b32_e32 v99, v177
	v_mov_b32_e32 v98, v29
	s_waitcnt lgkmcnt(0)
	v_pk_mul_f32 v[28:29], v[98:99], s[70:71]
	s_nop 0
	v_add_f32_e32 v32, v28, v29
.LBB0_1017:
	s_or_b64 exec, exec, s[0:1]
	v_mov_b32_e32 v28, 0xf149f2ca
	v_mov_b32_e32 v29, 0xf149f2ca
	s_and_saveexec_b64 s[0:1], s[6:7]
	s_cbranch_execz .LBB0_1019
	v_mov_b32_e32 v99, v178
	v_mov_b32_e32 v98, v30
	s_waitcnt lgkmcnt(0)
	v_pk_mul_f32 v[98:99], v[98:99], s[70:71]
	s_nop 0
	v_add_f32_e32 v29, v98, v99
.LBB0_1019:
	s_or_b64 exec, exec, s[0:1]
	s_and_saveexec_b64 s[0:1], s[8:9]
	s_cbranch_execz .LBB0_1021
	v_mov_b32_e32 v99, v179
	v_mov_b32_e32 v98, v31
	s_waitcnt lgkmcnt(0)
	v_pk_mul_f32 v[30:31], v[98:99], s[70:71]
	s_nop 0
	v_add_f32_e32 v28, v30, v31
.LBB0_1021:
	s_or_b64 exec, exec, s[0:1]
	v_mov_b32_e32 v30, 0xf149f2ca
	v_mov_b32_e32 v31, 0xf149f2ca
	s_and_saveexec_b64 s[0:1], s[10:11]
	s_cbranch_execz .LBB0_1023
	v_mov_b32_e32 v99, v180
	v_mov_b32_e32 v98, v24
	s_waitcnt lgkmcnt(0)
	v_pk_mul_f32 v[98:99], v[98:99], s[70:71]
	s_nop 0
	v_add_f32_e32 v31, v98, v99
.LBB0_1023:
	s_or_b64 exec, exec, s[0:1]
	s_and_saveexec_b64 s[0:1], s[12:13]
	s_cbranch_execz .LBB0_1025
	v_mov_b32_e32 v99, v181
	v_mov_b32_e32 v98, v25
	s_waitcnt lgkmcnt(0)
	v_pk_mul_f32 v[24:25], v[98:99], s[70:71]
	s_nop 0
	v_add_f32_e32 v30, v24, v25
.LBB0_1025:
	s_or_b64 exec, exec, s[0:1]
	v_mov_b32_e32 v25, 0xf149f2ca
	v_mov_b32_e32 v35, 0xf149f2ca
	s_and_saveexec_b64 s[0:1], s[14:15]
	s_cbranch_execz .LBB0_1027
	v_mov_b32_e32 v99, v182
	v_mov_b32_e32 v98, v26
	s_waitcnt lgkmcnt(0)
	v_pk_mul_f32 v[98:99], v[98:99], s[70:71]
	s_nop 0
	v_add_f32_e32 v35, v98, v99
.LBB0_1027:
	s_or_b64 exec, exec, s[0:1]
	s_and_saveexec_b64 s[0:1], s[16:17]
	s_cbranch_execz .LBB0_1029
	v_mov_b32_e32 v25, v183
	v_mov_b32_e32 v24, v27
	s_waitcnt lgkmcnt(0)
	v_pk_mul_f32 v[24:25], v[24:25], s[70:71]
	s_nop 0
	v_add_f32_e32 v25, v24, v25
.LBB0_1029:
	s_or_b64 exec, exec, s[0:1]
	v_mov_b32_e32 v24, 0xf149f2ca
	v_mov_b32_e32 v26, 0xf149f2ca
	ds_read_b32 v176, v72 offset:1116
	ds_read_b32 v177, v90 offset:1116
	ds_read_b32 v178, v91 offset:1116
	ds_read_b32 v179, v92 offset:1116
	ds_read_b32 v180, v94 offset:1116
	ds_read_b32 v181, v95 offset:1116
	ds_read_b32 v182, v96 offset:1116
	ds_read_b32 v183, v97 offset:1116
	s_waitcnt lgkmcnt(0)
	s_and_saveexec_b64 s[0:1], vcc
	s_cbranch_execz .LBB0_1031
	v_mov_b32_e32 v27, v176
	v_mov_b32_e32 v26, v20
	s_waitcnt lgkmcnt(0)
	v_pk_mul_f32 v[26:27], v[26:27], s[70:71]
	s_nop 0
	v_add_f32_e32 v26, v26, v27
.LBB0_1031:
	s_or_b64 exec, exec, s[0:1]
	s_and_saveexec_b64 s[0:1], s[4:5]
	s_cbranch_execz .LBB0_1033
	v_mov_b32_e32 v99, v177
	v_mov_b32_e32 v98, v21
	s_waitcnt lgkmcnt(0)
	v_pk_mul_f32 v[20:21], v[98:99], s[70:71]
	s_nop 0
	v_add_f32_e32 v24, v20, v21
.LBB0_1033:
	s_or_b64 exec, exec, s[0:1]
	v_mov_b32_e32 v20, 0xf149f2ca
	v_mov_b32_e32 v21, 0xf149f2ca
	s_and_saveexec_b64 s[0:1], s[6:7]
	s_cbranch_execz .LBB0_1035
	v_mov_b32_e32 v99, v178
	v_mov_b32_e32 v98, v22
	s_waitcnt lgkmcnt(0)
	v_pk_mul_f32 v[98:99], v[98:99], s[70:71]
	s_nop 0
	v_add_f32_e32 v21, v98, v99
.LBB0_1035:
	s_or_b64 exec, exec, s[0:1]
	s_and_saveexec_b64 s[0:1], s[8:9]
	s_cbranch_execz .LBB0_1037
	v_mov_b32_e32 v99, v179
	v_mov_b32_e32 v98, v23
	s_waitcnt lgkmcnt(0)
	v_pk_mul_f32 v[22:23], v[98:99], s[70:71]
	s_nop 0
	v_add_f32_e32 v20, v22, v23
.LBB0_1037:
	s_or_b64 exec, exec, s[0:1]
	v_mov_b32_e32 v22, 0xf149f2ca
	v_mov_b32_e32 v23, 0xf149f2ca
	s_and_saveexec_b64 s[0:1], s[10:11]
	s_cbranch_execz .LBB0_1039
	v_mov_b32_e32 v99, v180
	v_mov_b32_e32 v98, v16
	s_waitcnt lgkmcnt(0)
	v_pk_mul_f32 v[98:99], v[98:99], s[70:71]
	s_nop 0
	v_add_f32_e32 v23, v98, v99
.LBB0_1039:
	s_or_b64 exec, exec, s[0:1]
	s_and_saveexec_b64 s[0:1], s[12:13]
	s_cbranch_execz .LBB0_1041
	v_mov_b32_e32 v99, v181
	v_mov_b32_e32 v98, v17
	s_waitcnt lgkmcnt(0)
	v_pk_mul_f32 v[16:17], v[98:99], s[70:71]
	s_nop 0
	v_add_f32_e32 v22, v16, v17
.LBB0_1041:
	s_or_b64 exec, exec, s[0:1]
	v_mov_b32_e32 v27, 0xf149f2ca
	v_mov_b32_e32 v98, 0xf149f2ca
	s_and_saveexec_b64 s[0:1], s[14:15]
	s_cbranch_execz .LBB0_1043
	v_mov_b32_e32 v17, v182
	v_mov_b32_e32 v16, v18
	s_waitcnt lgkmcnt(0)
	v_pk_mul_f32 v[16:17], v[16:17], s[70:71]
	s_nop 0
	v_add_f32_e32 v98, v16, v17
.LBB0_1043:
	s_or_b64 exec, exec, s[0:1]
	s_and_saveexec_b64 s[0:1], s[16:17]
	s_cbranch_execz .LBB0_1045
	v_mov_b32_e32 v17, v183
	v_mov_b32_e32 v16, v19
	s_waitcnt lgkmcnt(0)
	v_pk_mul_f32 v[16:17], v[16:17], s[70:71]
	s_nop 0
	v_add_f32_e32 v27, v16, v17
.LBB0_1045:
	s_or_b64 exec, exec, s[0:1]
	v_mov_b32_e32 v16, 0xf149f2ca
	v_mov_b32_e32 v17, 0xf149f2ca
	ds_read_b32 v176, v72 offset:1240
	ds_read_b32 v177, v90 offset:1240
	ds_read_b32 v178, v91 offset:1240
	ds_read_b32 v179, v92 offset:1240
	ds_read_b32 v180, v94 offset:1240
	ds_read_b32 v181, v95 offset:1240
	ds_read_b32 v182, v96 offset:1240
	ds_read_b32 v183, v97 offset:1240
	s_waitcnt lgkmcnt(0)
	s_and_saveexec_b64 s[0:1], vcc
	s_cbranch_execz .LBB0_1047
	v_mov_b32_e32 v19, v176
	v_mov_b32_e32 v18, v12
	s_waitcnt lgkmcnt(0)
	v_pk_mul_f32 v[18:19], v[18:19], s[70:71]
	s_nop 0
	v_add_f32_e32 v17, v18, v19
.LBB0_1047:
	s_or_b64 exec, exec, s[0:1]
	s_and_saveexec_b64 s[0:1], s[4:5]
	s_cbranch_execz .LBB0_1049
	v_mov_b32_e32 v19, v177
	v_mov_b32_e32 v18, v13
	s_waitcnt lgkmcnt(0)
	v_pk_mul_f32 v[12:13], v[18:19], s[70:71]
	s_nop 0
	v_add_f32_e32 v16, v12, v13
.LBB0_1049:
	s_or_b64 exec, exec, s[0:1]
	v_mov_b32_e32 v12, 0xf149f2ca
	v_mov_b32_e32 v13, 0xf149f2ca
	s_and_saveexec_b64 s[0:1], s[6:7]
	s_cbranch_execz .LBB0_1051
	v_mov_b32_e32 v19, v178
	v_mov_b32_e32 v18, v14
	s_waitcnt lgkmcnt(0)
	v_pk_mul_f32 v[18:19], v[18:19], s[70:71]
	s_nop 0
	v_add_f32_e32 v13, v18, v19
.LBB0_1051:
	s_or_b64 exec, exec, s[0:1]
	s_and_saveexec_b64 s[0:1], s[8:9]
	s_cbranch_execz .LBB0_1053
	v_mov_b32_e32 v19, v179
	v_mov_b32_e32 v18, v15
	s_waitcnt lgkmcnt(0)
	v_pk_mul_f32 v[14:15], v[18:19], s[70:71]
	s_nop 0
	v_add_f32_e32 v12, v14, v15
.LBB0_1053:
	s_or_b64 exec, exec, s[0:1]
	v_mov_b32_e32 v14, 0xf149f2ca
	v_mov_b32_e32 v15, 0xf149f2ca
	s_and_saveexec_b64 s[0:1], s[10:11]
	s_cbranch_execz .LBB0_1055
	v_mov_b32_e32 v19, v180
	v_mov_b32_e32 v18, v8
	s_waitcnt lgkmcnt(0)
	v_pk_mul_f32 v[18:19], v[18:19], s[70:71]
	s_nop 0
	v_add_f32_e32 v15, v18, v19
.LBB0_1055:
	s_or_b64 exec, exec, s[0:1]
	s_and_saveexec_b64 s[0:1], s[12:13]
	s_cbranch_execz .LBB0_1057
	v_mov_b32_e32 v19, v181
	v_mov_b32_e32 v18, v9
	s_waitcnt lgkmcnt(0)
	v_pk_mul_f32 v[8:9], v[18:19], s[70:71]
	s_nop 0
	v_add_f32_e32 v14, v8, v9
.LBB0_1057:
	s_or_b64 exec, exec, s[0:1]
	v_mov_b32_e32 v18, 0xf149f2ca
	v_mov_b32_e32 v19, 0xf149f2ca
	s_and_saveexec_b64 s[0:1], s[14:15]
	s_cbranch_execz .LBB0_1059
	v_mov_b32_e32 v9, v182
	v_mov_b32_e32 v8, v10
	s_waitcnt lgkmcnt(0)
	v_pk_mul_f32 v[8:9], v[8:9], s[70:71]
	s_nop 0
	v_add_f32_e32 v19, v8, v9
.LBB0_1059:
	s_or_b64 exec, exec, s[0:1]
	s_and_saveexec_b64 s[0:1], s[16:17]
	s_cbranch_execz .LBB0_1061
	v_mov_b32_e32 v9, v183
	v_mov_b32_e32 v8, v11
	s_waitcnt lgkmcnt(0)
	v_pk_mul_f32 v[8:9], v[8:9], s[70:71]
	s_nop 0
	v_add_f32_e32 v18, v8, v9

.LBB0_1106:
	s_or_b64 exec, exec, s[0:1]
	v_mov_b32_e32 v66, 0xf149f2ca
	v_mov_b32_e32 v67, 0xf149f2ca
	ds_read_b32 v176, v88 offset:496
	ds_read_b32 v177, v89 offset:496
	ds_read_b32 v178, v91 offset:496
	ds_read_b32 v179, v92 offset:496
	ds_read_b32 v180, v93 offset:496
	ds_read_b32 v181, v94 offset:496
	ds_read_b32 v182, v95 offset:496
	ds_read_b32 v183, v96 offset:496
	s_waitcnt lgkmcnt(0)
	s_and_saveexec_b64 s[0:1], vcc
	s_cbranch_execz .LBB0_1108
	v_mov_b32_e32 v99, v176
	s_mov_b32 s58, 0x3e38aa3b
	v_mov_b32_e32 v98, v60
	s_mov_b32 s59, 0x3fb8aa3b
	s_waitcnt lgkmcnt(0)
	v_pk_mul_f32 v[98:99], v[98:99], s[58:59]
	s_nop 0
	v_add_f32_e32 v67, v98, v99
.LBB0_1108:
	s_or_b64 exec, exec, s[0:1]
	s_and_saveexec_b64 s[0:1], s[8:9]
	s_cbranch_execz .LBB0_1110
	v_mov_b32_e32 v99, v177
	s_mov_b32 s58, 0x3e38aa3b
	v_mov_b32_e32 v98, v61
	s_mov_b32 s59, 0x3fb8aa3b
	s_waitcnt lgkmcnt(0)
	v_pk_mul_f32 v[60:61], v[98:99], s[58:59]
	s_nop 0
	v_add_f32_e32 v66, v60, v61
.LBB0_1110:
	s_or_b64 exec, exec, s[0:1]
	v_mov_b32_e32 v60, 0xf149f2ca
	v_mov_b32_e32 v61, 0xf149f2ca
	s_and_saveexec_b64 s[0:1], s[10:11]
	s_cbranch_execz .LBB0_1112
	v_mov_b32_e32 v99, v178
	s_mov_b32 s58, 0x3e38aa3b
	v_mov_b32_e32 v98, v62
	s_mov_b32 s59, 0x3fb8aa3b
	s_waitcnt lgkmcnt(0)
	v_pk_mul_f32 v[98:99], v[98:99], s[58:59]
	s_nop 0
	v_add_f32_e32 v61, v98, v99
.LBB0_1112:
	s_or_b64 exec, exec, s[0:1]
	s_and_saveexec_b64 s[0:1], s[12:13]
	s_cbranch_execz .LBB0_1114
	v_mov_b32_e32 v99, v179
	s_mov_b32 s58, 0x3e38aa3b
	v_mov_b32_e32 v98, v63
	s_mov_b32 s59, 0x3fb8aa3b
	s_waitcnt lgkmcnt(0)
	v_pk_mul_f32 v[62:63], v[98:99], s[58:59]
	s_nop 0
	v_add_f32_e32 v60, v62, v63
.LBB0_1114:
	s_or_b64 exec, exec, s[0:1]
	v_mov_b32_e32 v62, 0xf149f2ca
	v_mov_b32_e32 v63, 0xf149f2ca
	s_and_saveexec_b64 s[0:1], s[14:15]
	s_cbranch_execz .LBB0_1116
	v_mov_b32_e32 v99, v180
	s_mov_b32 s58, 0x3e38aa3b
	v_mov_b32_e32 v98, v56
	s_mov_b32 s59, 0x3fb8aa3b
	s_waitcnt lgkmcnt(0)
	v_pk_mul_f32 v[98:99], v[98:99], s[58:59]
	s_nop 0
	v_add_f32_e32 v63, v98, v99
.LBB0_1116:
	s_or_b64 exec, exec, s[0:1]
	s_and_saveexec_b64 s[0:1], s[16:17]
	s_cbranch_execz .LBB0_1118
	v_mov_b32_e32 v99, v181
	s_mov_b32 s58, 0x3e38aa3b
	v_mov_b32_e32 v98, v57
	s_mov_b32 s59, 0x3fb8aa3b
	s_waitcnt lgkmcnt(0)
	v_pk_mul_f32 v[56:57], v[98:99], s[58:59]
	s_nop 0
	v_add_f32_e32 v62, v56, v57
.LBB0_1118:
	s_or_b64 exec, exec, s[0:1]
	v_mov_b32_e32 v56, 0xf149f2ca
	v_mov_b32_e32 v90, 0xf149f2ca
	s_and_saveexec_b64 s[0:1], s[18:19]
	s_cbranch_execz .LBB0_1120
	v_mov_b32_e32 v99, v182
	s_mov_b32 s58, 0x3e38aa3b
	v_mov_b32_e32 v98, v58
	s_mov_b32 s59, 0x3fb8aa3b
	s_waitcnt lgkmcnt(0)
	v_pk_mul_f32 v[98:99], v[98:99], s[58:59]
	s_nop 0
	v_add_f32_e32 v90, v98, v99
.LBB0_1120:
	s_or_b64 exec, exec, s[0:1]
	s_and_saveexec_b64 s[0:1], s[20:21]
	s_cbranch_execz .LBB0_1122
	v_mov_b32_e32 v57, v183
	s_mov_b32 s58, 0x3e38aa3b
	v_mov_b32_e32 v56, v59
	s_mov_b32 s59, 0x3fb8aa3b
	s_waitcnt lgkmcnt(0)
	v_pk_mul_f32 v[56:57], v[56:57], s[58:59]
	s_nop 0
	v_add_f32_e32 v56, v56, v57
.LBB0_1122:
	s_or_b64 exec, exec, s[0:1]
	v_mov_b32_e32 v57, 0xf149f2ca
	v_mov_b32_e32 v58, 0xf149f2ca
	ds_read_b32 v176, v88 offset:620
	ds_read_b32 v177, v89 offset:620
	ds_read_b32 v178, v91 offset:620
	ds_read_b32 v179, v92 offset:620
	ds_read_b32 v180, v93 offset:620
	ds_read_b32 v181, v94 offset:620
	ds_read_b32 v182, v95 offset:620
	ds_read_b32 v183, v96 offset:620
	s_waitcnt lgkmcnt(0)
	s_and_saveexec_b64 s[0:1], vcc
	s_cbranch_execz .LBB0_1124
	v_mov_b32_e32 v59, v176
	s_mov_b32 s58, 0x3e38aa3b
	v_mov_b32_e32 v58, v52
	s_mov_b32 s59, 0x3fb8aa3b
	s_waitcnt lgkmcnt(0)
	v_pk_mul_f32 v[58:59], v[58:59], s[58:59]
	s_nop 0
	v_add_f32_e32 v58, v58, v59
.LBB0_1124:
	s_or_b64 exec, exec, s[0:1]
	s_and_saveexec_b64 s[0:1], s[8:9]
	s_cbranch_execz .LBB0_1126
	v_mov_b32_e32 v99, v177
	s_mov_b32 s58, 0x3e38aa3b
	v_mov_b32_e32 v98, v53
	s_mov_b32 s59, 0x3fb8aa3b
	s_waitcnt lgkmcnt(0)
	v_pk_mul_f32 v[52:53], v[98:99], s[58:59]
	s_nop 0
	v_add_f32_e32 v57, v52, v53
.LBB0_1126:
	s_or_b64 exec, exec, s[0:1]
	v_mov_b32_e32 v52, 0xf149f2ca
	v_mov_b32_e32 v53, 0xf149f2ca
	s_and_saveexec_b64 s[0:1], s[10:11]
	s_cbranch_execz .LBB0_1128
	v_mov_b32_e32 v99, v178
	s_mov_b32 s58, 0x3e38aa3b
	v_mov_b32_e32 v98, v54
	s_mov_b32 s59, 0x3fb8aa3b
	s_waitcnt lgkmcnt(0)
	v_pk_mul_f32 v[98:99], v[98:99], s[58:59]
	s_nop 0
	v_add_f32_e32 v53, v98, v99
.LBB0_1128:
	s_or_b64 exec, exec, s[0:1]
	s_and_saveexec_b64 s[0:1], s[12:13]
	s_cbranch_execz .LBB0_1130
	v_mov_b32_e32 v99, v179
	s_mov_b32 s58, 0x3e38aa3b
	v_mov_b32_e32 v98, v55
	s_mov_b32 s59, 0x3fb8aa3b
	s_waitcnt lgkmcnt(0)
	v_pk_mul_f32 v[54:55], v[98:99], s[58:59]
	s_nop 0
	v_add_f32_e32 v52, v54, v55
.LBB0_1130:
	s_or_b64 exec, exec, s[0:1]
	v_mov_b32_e32 v54, 0xf149f2ca
	v_mov_b32_e32 v55, 0xf149f2ca
	s_and_saveexec_b64 s[0:1], s[14:15]
	s_cbranch_execz .LBB0_1132
	v_mov_b32_e32 v99, v180
	s_mov_b32 s58, 0x3e38aa3b
	v_mov_b32_e32 v98, v48
	s_mov_b32 s59, 0x3fb8aa3b
	s_waitcnt lgkmcnt(0)
	v_pk_mul_f32 v[98:99], v[98:99], s[58:59]
	s_nop 0
	v_add_f32_e32 v55, v98, v99
.LBB0_1132:
	s_or_b64 exec, exec, s[0:1]
	s_and_saveexec_b64 s[0:1], s[16:17]
	s_cbranch_execz .LBB0_1134
	v_mov_b32_e32 v99, v181
	s_mov_b32 s58, 0x3e38aa3b
	v_mov_b32_e32 v98, v49
	s_mov_b32 s59, 0x3fb8aa3b
	s_waitcnt lgkmcnt(0)
	v_pk_mul_f32 v[48:49], v[98:99], s[58:59]
	s_nop 0
	v_add_f32_e32 v54, v48, v49
.LBB0_1134:
	s_or_b64 exec, exec, s[0:1]
	v_mov_b32_e32 v48, 0xf149f2ca
	v_mov_b32_e32 v59, 0xf149f2ca
	s_and_saveexec_b64 s[0:1], s[18:19]
	s_cbranch_execz .LBB0_1136
	v_mov_b32_e32 v99, v182
	s_mov_b32 s58, 0x3e38aa3b
	v_mov_b32_e32 v98, v50
	s_mov_b32 s59, 0x3fb8aa3b
	s_waitcnt lgkmcnt(0)
	v_pk_mul_f32 v[98:99], v[98:99], s[58:59]
	s_nop 0
	v_add_f32_e32 v59, v98, v99
.LBB0_1136:
	s_or_b64 exec, exec, s[0:1]
	s_and_saveexec_b64 s[0:1], s[20:21]
	s_cbranch_execz .LBB0_1138
	v_mov_b32_e32 v49, v183
	s_mov_b32 s58, 0x3e38aa3b
	v_mov_b32_e32 v48, v51
	s_mov_b32 s59, 0x3fb8aa3b
	s_waitcnt lgkmcnt(0)
	v_pk_mul_f32 v[48:49], v[48:49], s[58:59]
	s_nop 0
	v_add_f32_e32 v48, v48, v49
.LBB0_1138:
	s_or_b64 exec, exec, s[0:1]
	v_mov_b32_e32 v49, 0xf149f2ca
	v_mov_b32_e32 v50, 0xf149f2ca
	ds_read_b32 v176, v88 offset:744
	ds_read_b32 v177, v89 offset:744
	ds_read_b32 v178, v91 offset:744
	ds_read_b32 v179, v92 offset:744
	ds_read_b32 v180, v93 offset:744
	ds_read_b32 v181, v94 offset:744
	ds_read_b32 v182, v95 offset:744
	ds_read_b32 v183, v96 offset:744
	s_waitcnt lgkmcnt(0)
	s_and_saveexec_b64 s[0:1], vcc
	s_cbranch_execz .LBB0_1140
	v_mov_b32_e32 v51, v176
	s_mov_b32 s58, 0x3e38aa3b
	v_mov_b32_e32 v50, v44
	s_mov_b32 s59, 0x3fb8aa3b
	s_waitcnt lgkmcnt(0)
	v_pk_mul_f32 v[50:51], v[50:51], s[58:59]
	s_nop 0
	v_add_f32_e32 v50, v50, v51
.LBB0_1140:
	s_or_b64 exec, exec, s[0:1]
	s_and_saveexec_b64 s[0:1], s[8:9]
	s_cbranch_execz .LBB0_1142
	v_mov_b32_e32 v99, v177
	s_mov_b32 s58, 0x3e38aa3b
	v_mov_b32_e32 v98, v45
	s_mov_b32 s59, 0x3fb8aa3b
	s_waitcnt lgkmcnt(0)
	v_pk_mul_f32 v[44:45], v[98:99], s[58:59]
	s_nop 0
	v_add_f32_e32 v49, v44, v45
.LBB0_1142:
	s_or_b64 exec, exec, s[0:1]
	v_mov_b32_e32 v44, 0xf149f2ca
	v_mov_b32_e32 v45, 0xf149f2ca
	s_and_saveexec_b64 s[0:1], s[10:11]
	s_cbranch_execz .LBB0_1144
	v_mov_b32_e32 v99, v178
	s_mov_b32 s58, 0x3e38aa3b
	v_mov_b32_e32 v98, v46
	s_mov_b32 s59, 0x3fb8aa3b
	s_waitcnt lgkmcnt(0)
	v_pk_mul_f32 v[98:99], v[98:99], s[58:59]
	s_nop 0
	v_add_f32_e32 v45, v98, v99
.LBB0_1144:
	s_or_b64 exec, exec, s[0:1]
	s_and_saveexec_b64 s[0:1], s[12:13]
	s_cbranch_execz .LBB0_1146
	v_mov_b32_e32 v99, v179
	s_mov_b32 s58, 0x3e38aa3b
	v_mov_b32_e32 v98, v47
	s_mov_b32 s59, 0x3fb8aa3b
	s_waitcnt lgkmcnt(0)
	v_pk_mul_f32 v[46:47], v[98:99], s[58:59]
	s_nop 0
	v_add_f32_e32 v44, v46, v47
.LBB0_1146:
	s_or_b64 exec, exec, s[0:1]
	v_mov_b32_e32 v46, 0xf149f2ca
	v_mov_b32_e32 v47, 0xf149f2ca
	s_and_saveexec_b64 s[0:1], s[14:15]
	s_cbranch_execz .LBB0_1148
	v_mov_b32_e32 v99, v180
	s_mov_b32 s58, 0x3e38aa3b
	v_mov_b32_e32 v98, v40
	s_mov_b32 s59, 0x3fb8aa3b
	s_waitcnt lgkmcnt(0)
	v_pk_mul_f32 v[98:99], v[98:99], s[58:59]
	s_nop 0
	v_add_f32_e32 v47, v98, v99
.LBB0_1148:
	s_or_b64 exec, exec, s[0:1]
	s_and_saveexec_b64 s[0:1], s[16:17]
	s_cbranch_execz .LBB0_1150
	v_mov_b32_e32 v99, v181
	s_mov_b32 s58, 0x3e38aa3b
	v_mov_b32_e32 v98, v41
	s_mov_b32 s59, 0x3fb8aa3b
	s_waitcnt lgkmcnt(0)
	v_pk_mul_f32 v[40:41], v[98:99], s[58:59]
	s_nop 0
	v_add_f32_e32 v46, v40, v41
.LBB0_1150:
	s_or_b64 exec, exec, s[0:1]
	v_mov_b32_e32 v40, 0xf149f2ca
	v_mov_b32_e32 v51, 0xf149f2ca
	s_and_saveexec_b64 s[0:1], s[18:19]
	s_cbranch_execz .LBB0_1152
	v_mov_b32_e32 v99, v182
	s_mov_b32 s58, 0x3e38aa3b
	v_mov_b32_e32 v98, v42
	s_mov_b32 s59, 0x3fb8aa3b
	s_waitcnt lgkmcnt(0)
	v_pk_mul_f32 v[98:99], v[98:99], s[58:59]
	s_nop 0
	v_add_f32_e32 v51, v98, v99
.LBB0_1152:
	s_or_b64 exec, exec, s[0:1]
	s_and_saveexec_b64 s[0:1], s[20:21]
	s_cbranch_execz .LBB0_1154
	v_mov_b32_e32 v41, v183
	s_mov_b32 s58, 0x3e38aa3b
	v_mov_b32_e32 v40, v43
	s_mov_b32 s59, 0x3fb8aa3b
	s_waitcnt lgkmcnt(0)
	v_pk_mul_f32 v[40:41], v[40:41], s[58:59]
	s_nop 0
	v_add_f32_e32 v40, v40, v41
.LBB0_1154:
	s_or_b64 exec, exec, s[0:1]
	v_mov_b32_e32 v41, 0xf149f2ca
	v_mov_b32_e32 v42, 0xf149f2ca
	ds_read_b32 v176, v88 offset:868
	ds_read_b32 v177, v89 offset:868
	ds_read_b32 v178, v91 offset:868
	ds_read_b32 v179, v92 offset:868
	ds_read_b32 v180, v93 offset:868
	ds_read_b32 v181, v94 offset:868
	ds_read_b32 v182, v95 offset:868
	ds_read_b32 v183, v96 offset:868
	s_waitcnt lgkmcnt(0)
	s_and_saveexec_b64 s[0:1], vcc
	s_cbranch_execz .LBB0_1156
	v_mov_b32_e32 v43, v176
	s_mov_b32 s58, 0x3e38aa3b
	v_mov_b32_e32 v42, v36
	s_mov_b32 s59, 0x3fb8aa3b
	s_waitcnt lgkmcnt(0)
	v_pk_mul_f32 v[42:43], v[42:43], s[58:59]
	s_nop 0
	v_add_f32_e32 v42, v42, v43
.LBB0_1156:
	s_or_b64 exec, exec, s[0:1]
	s_and_saveexec_b64 s[0:1], s[8:9]
	s_cbranch_execz .LBB0_1158
	v_mov_b32_e32 v99, v177
	s_mov_b32 s58, 0x3e38aa3b
	v_mov_b32_e32 v98, v37
	s_mov_b32 s59, 0x3fb8aa3b
	s_waitcnt lgkmcnt(0)
	v_pk_mul_f32 v[36:37], v[98:99], s[58:59]
	s_nop 0
	v_add_f32_e32 v41, v36, v37
.LBB0_1158:
	s_or_b64 exec, exec, s[0:1]
	v_mov_b32_e32 v36, 0xf149f2ca
	v_mov_b32_e32 v37, 0xf149f2ca
	s_and_saveexec_b64 s[0:1], s[10:11]
	s_cbranch_execz .LBB0_1160
	v_mov_b32_e32 v99, v178
	s_mov_b32 s58, 0x3e38aa3b
	v_mov_b32_e32 v98, v38
	s_mov_b32 s59, 0x3fb8aa3b
	s_waitcnt lgkmcnt(0)
	v_pk_mul_f32 v[98:99], v[98:99], s[58:59]
	s_nop 0
	v_add_f32_e32 v37, v98, v99
.LBB0_1160:
	s_or_b64 exec, exec, s[0:1]
	s_and_saveexec_b64 s[0:1], s[12:13]
	s_cbranch_execz .LBB0_1162
	v_mov_b32_e32 v99, v179
	s_mov_b32 s58, 0x3e38aa3b
	v_mov_b32_e32 v98, v39
	s_mov_b32 s59, 0x3fb8aa3b
	s_waitcnt lgkmcnt(0)
	v_pk_mul_f32 v[38:39], v[98:99], s[58:59]
	s_nop 0
	v_add_f32_e32 v36, v38, v39
.LBB0_1162:
	s_or_b64 exec, exec, s[0:1]
	v_mov_b32_e32 v38, 0xf149f2ca
	v_mov_b32_e32 v39, 0xf149f2ca
	s_and_saveexec_b64 s[0:1], s[14:15]
	s_cbranch_execz .LBB0_1164
	v_mov_b32_e32 v99, v180
	s_mov_b32 s58, 0x3e38aa3b
	v_mov_b32_e32 v98, v32
	s_mov_b32 s59, 0x3fb8aa3b
	s_waitcnt lgkmcnt(0)
	v_pk_mul_f32 v[98:99], v[98:99], s[58:59]
	s_nop 0
	v_add_f32_e32 v39, v98, v99
.LBB0_1164:
	s_or_b64 exec, exec, s[0:1]
	s_and_saveexec_b64 s[0:1], s[16:17]
	s_cbranch_execz .LBB0_1166
	v_mov_b32_e32 v99, v181
	s_mov_b32 s58, 0x3e38aa3b
	v_mov_b32_e32 v98, v33
	s_mov_b32 s59, 0x3fb8aa3b
	s_waitcnt lgkmcnt(0)
	v_pk_mul_f32 v[32:33], v[98:99], s[58:59]
	s_nop 0
	v_add_f32_e32 v38, v32, v33
.LBB0_1166:
	s_or_b64 exec, exec, s[0:1]
	v_mov_b32_e32 v32, 0xf149f2ca
	v_mov_b32_e32 v43, 0xf149f2ca
	s_and_saveexec_b64 s[0:1], s[18:19]
	s_cbranch_execz .LBB0_1168
	v_mov_b32_e32 v99, v182
	s_mov_b32 s58, 0x3e38aa3b
	v_mov_b32_e32 v98, v34
	s_mov_b32 s59, 0x3fb8aa3b
	s_waitcnt lgkmcnt(0)
	v_pk_mul_f32 v[98:99], v[98:99], s[58:59]
	s_nop 0
	v_add_f32_e32 v43, v98, v99
.LBB0_1168:
	s_or_b64 exec, exec, s[0:1]
	s_and_saveexec_b64 s[0:1], s[20:21]
	s_cbranch_execz .LBB0_1170
	v_mov_b32_e32 v33, v183
	s_mov_b32 s58, 0x3e38aa3b
	v_mov_b32_e32 v32, v35
	s_mov_b32 s59, 0x3fb8aa3b
	s_waitcnt lgkmcnt(0)
	v_pk_mul_f32 v[32:33], v[32:33], s[58:59]
	s_nop 0
	v_add_f32_e32 v32, v32, v33
.LBB0_1170:
	s_or_b64 exec, exec, s[0:1]
	v_mov_b32_e32 v33, 0xf149f2ca
	v_mov_b32_e32 v34, 0xf149f2ca
	ds_read_b32 v176, v88 offset:992
	ds_read_b32 v177, v89 offset:992
	ds_read_b32 v178, v91 offset:992
	ds_read_b32 v179, v92 offset:992
	ds_read_b32 v180, v93 offset:992
	ds_read_b32 v181, v94 offset:992
	ds_read_b32 v182, v95 offset:992
	ds_read_b32 v183, v96 offset:992
	s_waitcnt lgkmcnt(0)
	s_and_saveexec_b64 s[0:1], vcc
	s_cbranch_execz .LBB0_1172
	v_mov_b32_e32 v35, v176
	s_mov_b32 s58, 0x3e38aa3b
	v_mov_b32_e32 v34, v28
	s_mov_b32 s59, 0x3fb8aa3b
	s_waitcnt lgkmcnt(0)
	v_pk_mul_f32 v[34:35], v[34:35], s[58:59]
	s_nop 0
	v_add_f32_e32 v34, v34, v35
.LBB0_1172:
	s_or_b64 exec, exec, s[0:1]
	s_and_saveexec_b64 s[0:1], s[8:9]
	s_cbranch_execz .LBB0_1174
	v_mov_b32_e32 v99, v177
	s_mov_b32 s58, 0x3e38aa3b
	v_mov_b32_e32 v98, v29
	s_mov_b32 s59, 0x3fb8aa3b
	s_waitcnt lgkmcnt(0)
	v_pk_mul_f32 v[28:29], v[98:99], s[58:59]
	s_nop 0
	v_add_f32_e32 v33, v28, v29
.LBB0_1174:
	s_or_b64 exec, exec, s[0:1]
	v_mov_b32_e32 v28, 0xf149f2ca
	v_mov_b32_e32 v29, 0xf149f2ca
	s_and_saveexec_b64 s[0:1], s[10:11]
	s_cbranch_execz .LBB0_1176
	v_mov_b32_e32 v99, v178
	s_mov_b32 s58, 0x3e38aa3b
	v_mov_b32_e32 v98, v30
	s_mov_b32 s59, 0x3fb8aa3b
	s_waitcnt lgkmcnt(0)
	v_pk_mul_f32 v[98:99], v[98:99], s[58:59]
	s_nop 0
	v_add_f32_e32 v29, v98, v99
.LBB0_1176:
	s_or_b64 exec, exec, s[0:1]
	s_and_saveexec_b64 s[0:1], s[12:13]
	s_cbranch_execz .LBB0_1178
	v_mov_b32_e32 v99, v179
	s_mov_b32 s58, 0x3e38aa3b
	v_mov_b32_e32 v98, v31
	s_mov_b32 s59, 0x3fb8aa3b
	s_waitcnt lgkmcnt(0)
	v_pk_mul_f32 v[30:31], v[98:99], s[58:59]
	s_nop 0
	v_add_f32_e32 v28, v30, v31
.LBB0_1178:
	s_or_b64 exec, exec, s[0:1]
	v_mov_b32_e32 v30, 0xf149f2ca
	v_mov_b32_e32 v31, 0xf149f2ca
	s_and_saveexec_b64 s[0:1], s[14:15]
	s_cbranch_execz .LBB0_1180
	v_mov_b32_e32 v99, v180
	s_mov_b32 s58, 0x3e38aa3b
	v_mov_b32_e32 v98, v24
	s_mov_b32 s59, 0x3fb8aa3b
	s_waitcnt lgkmcnt(0)
	v_pk_mul_f32 v[98:99], v[98:99], s[58:59]
	s_nop 0
	v_add_f32_e32 v31, v98, v99
.LBB0_1180:
	s_or_b64 exec, exec, s[0:1]
	s_and_saveexec_b64 s[0:1], s[16:17]
	s_cbranch_execz .LBB0_1182
	v_mov_b32_e32 v99, v181
	s_mov_b32 s58, 0x3e38aa3b
	v_mov_b32_e32 v98, v25
	s_mov_b32 s59, 0x3fb8aa3b
	s_waitcnt lgkmcnt(0)
	v_pk_mul_f32 v[24:25], v[98:99], s[58:59]
	s_nop 0
	v_add_f32_e32 v30, v24, v25
.LBB0_1182:
	s_or_b64 exec, exec, s[0:1]
	v_mov_b32_e32 v24, 0xf149f2ca
	v_mov_b32_e32 v35, 0xf149f2ca
	s_and_saveexec_b64 s[0:1], s[18:19]
	s_cbranch_execz .LBB0_1184
	v_mov_b32_e32 v99, v182
	s_mov_b32 s58, 0x3e38aa3b
	v_mov_b32_e32 v98, v26
	s_mov_b32 s59, 0x3fb8aa3b
	s_waitcnt lgkmcnt(0)
	v_pk_mul_f32 v[98:99], v[98:99], s[58:59]
	s_nop 0
	v_add_f32_e32 v35, v98, v99
.LBB0_1184:
	s_or_b64 exec, exec, s[0:1]
	s_and_saveexec_b64 s[0:1], s[20:21]
	s_cbranch_execz .LBB0_1186
	v_mov_b32_e32 v25, v183
	s_mov_b32 s58, 0x3e38aa3b
	v_mov_b32_e32 v24, v27
	s_mov_b32 s59, 0x3fb8aa3b
	s_waitcnt lgkmcnt(0)
	v_pk_mul_f32 v[24:25], v[24:25], s[58:59]
	s_nop 0
	v_add_f32_e32 v24, v24, v25
.LBB0_1186:
	s_or_b64 exec, exec, s[0:1]
	v_mov_b32_e32 v25, 0xf149f2ca
	v_mov_b32_e32 v26, 0xf149f2ca
	ds_read_b32 v176, v88 offset:1116
	ds_read_b32 v177, v89 offset:1116
	ds_read_b32 v178, v91 offset:1116
	ds_read_b32 v179, v92 offset:1116
	ds_read_b32 v180, v93 offset:1116
	ds_read_b32 v181, v94 offset:1116
	ds_read_b32 v182, v95 offset:1116
	ds_read_b32 v183, v96 offset:1116
	s_waitcnt lgkmcnt(0)
	s_and_saveexec_b64 s[0:1], vcc
	s_cbranch_execz .LBB0_1188
	v_mov_b32_e32 v27, v176
	s_mov_b32 s58, 0x3e38aa3b
	v_mov_b32_e32 v26, v20
	s_mov_b32 s59, 0x3fb8aa3b
	s_waitcnt lgkmcnt(0)
	v_pk_mul_f32 v[26:27], v[26:27], s[58:59]
	s_nop 0
	v_add_f32_e32 v26, v26, v27
.LBB0_1188:
	s_or_b64 exec, exec, s[0:1]
	s_and_saveexec_b64 s[0:1], s[8:9]
	s_cbranch_execz .LBB0_1190
	v_mov_b32_e32 v99, v177
	s_mov_b32 s58, 0x3e38aa3b
	v_mov_b32_e32 v98, v21
	s_mov_b32 s59, 0x3fb8aa3b
	s_waitcnt lgkmcnt(0)
	v_pk_mul_f32 v[20:21], v[98:99], s[58:59]
	s_nop 0
	v_add_f32_e32 v25, v20, v21
.LBB0_1190:
	s_or_b64 exec, exec, s[0:1]
	v_mov_b32_e32 v20, 0xf149f2ca
	v_mov_b32_e32 v21, 0xf149f2ca
	s_and_saveexec_b64 s[0:1], s[10:11]
	s_cbranch_execz .LBB0_1192
	v_mov_b32_e32 v99, v178
	s_mov_b32 s58, 0x3e38aa3b
	v_mov_b32_e32 v98, v22
	s_mov_b32 s59, 0x3fb8aa3b
	s_waitcnt lgkmcnt(0)
	v_pk_mul_f32 v[98:99], v[98:99], s[58:59]
	s_nop 0
	v_add_f32_e32 v21, v98, v99
.LBB0_1192:
	s_or_b64 exec, exec, s[0:1]
	s_and_saveexec_b64 s[0:1], s[12:13]
	s_cbranch_execz .LBB0_1194
	v_mov_b32_e32 v99, v179
	s_mov_b32 s58, 0x3e38aa3b
	v_mov_b32_e32 v98, v23
	s_mov_b32 s59, 0x3fb8aa3b
	s_waitcnt lgkmcnt(0)
	v_pk_mul_f32 v[22:23], v[98:99], s[58:59]
	s_nop 0
	v_add_f32_e32 v20, v22, v23
.LBB0_1194:
	s_or_b64 exec, exec, s[0:1]
	v_mov_b32_e32 v22, 0xf149f2ca
	v_mov_b32_e32 v23, 0xf149f2ca
	s_and_saveexec_b64 s[0:1], s[14:15]
	s_cbranch_execz .LBB0_1196
	v_mov_b32_e32 v99, v180
	s_mov_b32 s58, 0x3e38aa3b
	v_mov_b32_e32 v98, v16
	s_mov_b32 s59, 0x3fb8aa3b
	s_waitcnt lgkmcnt(0)
	v_pk_mul_f32 v[98:99], v[98:99], s[58:59]
	s_nop 0
	v_add_f32_e32 v23, v98, v99
.LBB0_1196:
	s_or_b64 exec, exec, s[0:1]
	s_and_saveexec_b64 s[0:1], s[16:17]
	s_cbranch_execz .LBB0_1198
	v_mov_b32_e32 v99, v181
	s_mov_b32 s58, 0x3e38aa3b
	v_mov_b32_e32 v98, v17
	s_mov_b32 s59, 0x3fb8aa3b
	s_waitcnt lgkmcnt(0)
	v_pk_mul_f32 v[16:17], v[98:99], s[58:59]
	s_nop 0
	v_add_f32_e32 v22, v16, v17
.LBB0_1198:
	s_or_b64 exec, exec, s[0:1]
	v_mov_b32_e32 v17, 0xf149f2ca
	v_mov_b32_e32 v27, 0xf149f2ca
	s_and_saveexec_b64 s[0:1], s[18:19]
	s_cbranch_execz .LBB0_1200
	v_mov_b32_e32 v99, v182
	s_mov_b32 s58, 0x3e38aa3b
	v_mov_b32_e32 v98, v18
	s_mov_b32 s59, 0x3fb8aa3b
	s_waitcnt lgkmcnt(0)
	v_pk_mul_f32 v[98:99], v[98:99], s[58:59]
	s_nop 0
	v_add_f32_e32 v27, v98, v99
.LBB0_1200:
	s_or_b64 exec, exec, s[0:1]
	s_and_saveexec_b64 s[0:1], s[20:21]
	s_cbranch_execz .LBB0_1202
	v_mov_b32_e32 v17, v183
	s_mov_b32 s58, 0x3e38aa3b
	v_mov_b32_e32 v16, v19
	s_mov_b32 s59, 0x3fb8aa3b
	s_waitcnt lgkmcnt(0)
	v_pk_mul_f32 v[16:17], v[16:17], s[58:59]
	s_nop 0
	v_add_f32_e32 v17, v16, v17
.LBB0_1202:
	s_or_b64 exec, exec, s[0:1]
	v_mov_b32_e32 v16, 0xf149f2ca
	v_mov_b32_e32 v18, 0xf149f2ca
	ds_read_b32 v176, v88 offset:1240
	ds_read_b32 v177, v89 offset:1240
	ds_read_b32 v178, v91 offset:1240
	ds_read_b32 v179, v92 offset:1240
	ds_read_b32 v180, v93 offset:1240
	ds_read_b32 v181, v94 offset:1240
	ds_read_b32 v182, v95 offset:1240
	ds_read_b32 v183, v96 offset:1240
	s_waitcnt lgkmcnt(0)
	s_and_saveexec_b64 s[0:1], vcc
	s_cbranch_execz .LBB0_1204
	v_mov_b32_e32 v19, v176
	s_mov_b32 s58, 0x3e38aa3b
	v_mov_b32_e32 v18, v12
	s_mov_b32 s59, 0x3fb8aa3b
	s_waitcnt lgkmcnt(0)
	v_pk_mul_f32 v[18:19], v[18:19], s[58:59]
	s_nop 0
	v_add_f32_e32 v18, v18, v19

.LBB0_1214:
	s_or_b64 exec, exec, s[0:1]
	v_mov_b32_e32 v8, 0xf149f2ca
	v_mov_b32_e32 v9, 0xf149f2ca
	s_and_saveexec_b64 s[0:1], s[18:19]
	s_cbranch_execz .LBB0_1216
	v_mov_b32_e32 v89, v182
	s_mov_b32 s8, 0x3e38aa3b
	v_mov_b32_e32 v88, v10
	s_mov_b32 s9, 0x3fb8aa3b
	s_waitcnt lgkmcnt(0)
	v_pk_mul_f32 v[88:89], v[88:89], s[8:9]
	s_nop 0
	v_add_f32_e32 v9, v88, v89
.LBB0_1216:
	s_or_b64 exec, exec, s[0:1]
	s_lshr_b32 s0, s24, 3
	s_and_saveexec_b64 s[8:9], s[20:21]
	s_cbranch_execz .LBB0_1218
	v_mov_b32_e32 v89, v183
	s_mov_b32 s10, 0x3e38aa3b
	v_mov_b32_e32 v88, v11
	s_mov_b32 s11, 0x3fb8aa3b
	s_waitcnt lgkmcnt(0)
	v_pk_mul_f32 v[10:11], v[88:89], s[10:11]
	s_nop 0
	v_add_f32_e32 v8, v10, v11

.LBB0_1246:
	s_or_b64 exec, exec, s[0:1]
	v_mov_b32_e32 v66, 0xf149f2ca
	v_mov_b32_e32 v67, 0xf149f2ca
	ds_read_b32 v176, v88 offset:496
	ds_read_b32 v177, v89 offset:496
	ds_read_b32 v178, v90 offset:496
	ds_read_b32 v179, v91 offset:496
	ds_read_b32 v180, v92 offset:496
	ds_read_b32 v181, v94 offset:496
	ds_read_b32 v182, v95 offset:496
	ds_read_b32 v183, v96 offset:496
	s_waitcnt lgkmcnt(0)
	s_and_saveexec_b64 s[0:1], vcc
	s_cbranch_execz .LBB0_1248
	v_mov_b32_e32 v99, v176
	s_mov_b32 s24, 0x3e38aa3b
	v_mov_b32_e32 v98, v60
	s_mov_b32 s25, 0x3fb8aa3b
	s_waitcnt lgkmcnt(0)
	v_pk_mul_f32 v[98:99], v[98:99], s[24:25]
	s_nop 0
	v_add_f32_e32 v67, v98, v99
.LBB0_1248:
	s_or_b64 exec, exec, s[0:1]
	s_and_saveexec_b64 s[0:1], s[10:11]
	s_cbranch_execz .LBB0_1250
	v_mov_b32_e32 v99, v177
	s_mov_b32 s24, 0x3e38aa3b
	v_mov_b32_e32 v98, v61
	s_mov_b32 s25, 0x3fb8aa3b
	s_waitcnt lgkmcnt(0)
	v_pk_mul_f32 v[60:61], v[98:99], s[24:25]
	s_nop 0
	v_add_f32_e32 v66, v60, v61
.LBB0_1250:
	s_or_b64 exec, exec, s[0:1]
	v_mov_b32_e32 v60, 0xf149f2ca
	v_mov_b32_e32 v61, 0xf149f2ca
	s_and_saveexec_b64 s[0:1], s[12:13]
	s_cbranch_execz .LBB0_1252
	v_mov_b32_e32 v99, v178
	s_mov_b32 s24, 0x3e38aa3b
	v_mov_b32_e32 v98, v62
	s_mov_b32 s25, 0x3fb8aa3b
	s_waitcnt lgkmcnt(0)
	v_pk_mul_f32 v[98:99], v[98:99], s[24:25]
	s_nop 0
	v_add_f32_e32 v61, v98, v99
.LBB0_1252:
	s_or_b64 exec, exec, s[0:1]
	s_and_saveexec_b64 s[0:1], s[14:15]
	s_cbranch_execz .LBB0_1254
	v_mov_b32_e32 v99, v179
	s_mov_b32 s24, 0x3e38aa3b
	v_mov_b32_e32 v98, v63
	s_mov_b32 s25, 0x3fb8aa3b
	s_waitcnt lgkmcnt(0)
	v_pk_mul_f32 v[62:63], v[98:99], s[24:25]
	s_nop 0
	v_add_f32_e32 v60, v62, v63
.LBB0_1254:
	s_or_b64 exec, exec, s[0:1]
	v_mov_b32_e32 v62, 0xf149f2ca
	v_mov_b32_e32 v63, 0xf149f2ca
	s_and_saveexec_b64 s[0:1], s[16:17]
	s_cbranch_execz .LBB0_1256
	v_mov_b32_e32 v99, v180
	s_mov_b32 s24, 0x3e38aa3b
	v_mov_b32_e32 v98, v56
	s_mov_b32 s25, 0x3fb8aa3b
	s_waitcnt lgkmcnt(0)
	v_pk_mul_f32 v[98:99], v[98:99], s[24:25]
	s_nop 0
	v_add_f32_e32 v63, v98, v99
.LBB0_1256:
	s_or_b64 exec, exec, s[0:1]
	s_and_saveexec_b64 s[0:1], s[18:19]
	s_cbranch_execz .LBB0_1258
	v_mov_b32_e32 v99, v181
	s_mov_b32 s24, 0x3e38aa3b
	v_mov_b32_e32 v98, v57
	s_mov_b32 s25, 0x3fb8aa3b
	s_waitcnt lgkmcnt(0)
	v_pk_mul_f32 v[56:57], v[98:99], s[24:25]
	s_nop 0
	v_add_f32_e32 v62, v56, v57
.LBB0_1258:
	s_or_b64 exec, exec, s[0:1]
	v_mov_b32_e32 v56, 0xf149f2ca
	v_mov_b32_e32 v93, 0xf149f2ca
	s_and_saveexec_b64 s[0:1], s[20:21]
	s_cbranch_execz .LBB0_1260
	v_mov_b32_e32 v99, v182
	s_mov_b32 s24, 0x3e38aa3b
	v_mov_b32_e32 v98, v58
	s_mov_b32 s25, 0x3fb8aa3b
	s_waitcnt lgkmcnt(0)
	v_pk_mul_f32 v[98:99], v[98:99], s[24:25]
	s_nop 0
	v_add_f32_e32 v93, v98, v99
.LBB0_1260:
	s_or_b64 exec, exec, s[0:1]
	s_and_saveexec_b64 s[0:1], s[22:23]
	s_cbranch_execz .LBB0_1262
	v_mov_b32_e32 v57, v183
	s_mov_b32 s24, 0x3e38aa3b
	v_mov_b32_e32 v56, v59
	s_mov_b32 s25, 0x3fb8aa3b
	s_waitcnt lgkmcnt(0)
	v_pk_mul_f32 v[56:57], v[56:57], s[24:25]
	s_nop 0
	v_add_f32_e32 v56, v56, v57
.LBB0_1262:
	s_or_b64 exec, exec, s[0:1]
	v_mov_b32_e32 v57, 0xf149f2ca
	v_mov_b32_e32 v58, 0xf149f2ca
	ds_read_b32 v176, v88 offset:620
	ds_read_b32 v177, v89 offset:620
	ds_read_b32 v178, v90 offset:620
	ds_read_b32 v179, v91 offset:620
	ds_read_b32 v180, v92 offset:620
	ds_read_b32 v181, v94 offset:620
	ds_read_b32 v182, v95 offset:620
	ds_read_b32 v183, v96 offset:620
	s_waitcnt lgkmcnt(0)
	s_and_saveexec_b64 s[0:1], vcc
	s_cbranch_execz .LBB0_1264
	v_mov_b32_e32 v59, v176
	s_mov_b32 s24, 0x3e38aa3b
	v_mov_b32_e32 v58, v52
	s_mov_b32 s25, 0x3fb8aa3b
	s_waitcnt lgkmcnt(0)
	v_pk_mul_f32 v[58:59], v[58:59], s[24:25]
	s_nop 0
	v_add_f32_e32 v58, v58, v59
.LBB0_1264:
	s_or_b64 exec, exec, s[0:1]
	s_and_saveexec_b64 s[0:1], s[10:11]
	s_cbranch_execz .LBB0_1266
	v_mov_b32_e32 v99, v177
	s_mov_b32 s24, 0x3e38aa3b
	v_mov_b32_e32 v98, v53
	s_mov_b32 s25, 0x3fb8aa3b
	s_waitcnt lgkmcnt(0)
	v_pk_mul_f32 v[52:53], v[98:99], s[24:25]
	s_nop 0
	v_add_f32_e32 v57, v52, v53
.LBB0_1266:
	s_or_b64 exec, exec, s[0:1]
	v_mov_b32_e32 v52, 0xf149f2ca
	v_mov_b32_e32 v53, 0xf149f2ca
	s_and_saveexec_b64 s[0:1], s[12:13]
	s_cbranch_execz .LBB0_1268
	v_mov_b32_e32 v99, v178
	s_mov_b32 s24, 0x3e38aa3b
	v_mov_b32_e32 v98, v54
	s_mov_b32 s25, 0x3fb8aa3b
	s_waitcnt lgkmcnt(0)
	v_pk_mul_f32 v[98:99], v[98:99], s[24:25]
	s_nop 0
	v_add_f32_e32 v53, v98, v99
.LBB0_1268:
	s_or_b64 exec, exec, s[0:1]
	s_and_saveexec_b64 s[0:1], s[14:15]
	s_cbranch_execz .LBB0_1270
	v_mov_b32_e32 v99, v179
	s_mov_b32 s24, 0x3e38aa3b
	v_mov_b32_e32 v98, v55
	s_mov_b32 s25, 0x3fb8aa3b
	s_waitcnt lgkmcnt(0)
	v_pk_mul_f32 v[54:55], v[98:99], s[24:25]
	s_nop 0
	v_add_f32_e32 v52, v54, v55
.LBB0_1270:
	s_or_b64 exec, exec, s[0:1]
	v_mov_b32_e32 v54, 0xf149f2ca
	v_mov_b32_e32 v55, 0xf149f2ca
	s_and_saveexec_b64 s[0:1], s[16:17]
	s_cbranch_execz .LBB0_1272
	v_mov_b32_e32 v99, v180
	s_mov_b32 s24, 0x3e38aa3b
	v_mov_b32_e32 v98, v48
	s_mov_b32 s25, 0x3fb8aa3b
	s_waitcnt lgkmcnt(0)
	v_pk_mul_f32 v[98:99], v[98:99], s[24:25]
	s_nop 0
	v_add_f32_e32 v55, v98, v99
.LBB0_1272:
	s_or_b64 exec, exec, s[0:1]
	s_and_saveexec_b64 s[0:1], s[18:19]
	s_cbranch_execz .LBB0_1274
	v_mov_b32_e32 v99, v181
	s_mov_b32 s24, 0x3e38aa3b
	v_mov_b32_e32 v98, v49
	s_mov_b32 s25, 0x3fb8aa3b
	s_waitcnt lgkmcnt(0)
	v_pk_mul_f32 v[48:49], v[98:99], s[24:25]
	s_nop 0
	v_add_f32_e32 v54, v48, v49
.LBB0_1274:
	s_or_b64 exec, exec, s[0:1]
	v_mov_b32_e32 v48, 0xf149f2ca
	v_mov_b32_e32 v59, 0xf149f2ca
	s_and_saveexec_b64 s[0:1], s[20:21]
	s_cbranch_execz .LBB0_1276
	v_mov_b32_e32 v99, v182
	s_mov_b32 s24, 0x3e38aa3b
	v_mov_b32_e32 v98, v50
	s_mov_b32 s25, 0x3fb8aa3b
	s_waitcnt lgkmcnt(0)
	v_pk_mul_f32 v[98:99], v[98:99], s[24:25]
	s_nop 0
	v_add_f32_e32 v59, v98, v99
.LBB0_1276:
	s_or_b64 exec, exec, s[0:1]
	s_and_saveexec_b64 s[0:1], s[22:23]
	s_cbranch_execz .LBB0_1278
	v_mov_b32_e32 v49, v183
	s_mov_b32 s24, 0x3e38aa3b
	v_mov_b32_e32 v48, v51
	s_mov_b32 s25, 0x3fb8aa3b
	s_waitcnt lgkmcnt(0)
	v_pk_mul_f32 v[48:49], v[48:49], s[24:25]
	s_nop 0
	v_add_f32_e32 v48, v48, v49
.LBB0_1278:
	s_or_b64 exec, exec, s[0:1]
	v_mov_b32_e32 v49, 0xf149f2ca
	v_mov_b32_e32 v50, 0xf149f2ca
	ds_read_b32 v176, v88 offset:744
	ds_read_b32 v177, v89 offset:744
	ds_read_b32 v178, v90 offset:744
	ds_read_b32 v179, v91 offset:744
	ds_read_b32 v180, v92 offset:744
	ds_read_b32 v181, v94 offset:744
	ds_read_b32 v182, v95 offset:744
	ds_read_b32 v183, v96 offset:744
	s_waitcnt lgkmcnt(0)
	s_and_saveexec_b64 s[0:1], vcc
	s_cbranch_execz .LBB0_1280
	v_mov_b32_e32 v51, v176
	s_mov_b32 s24, 0x3e38aa3b
	v_mov_b32_e32 v50, v44
	s_mov_b32 s25, 0x3fb8aa3b
	s_waitcnt lgkmcnt(0)
	v_pk_mul_f32 v[50:51], v[50:51], s[24:25]
	s_nop 0
	v_add_f32_e32 v50, v50, v51
.LBB0_1280:
	s_or_b64 exec, exec, s[0:1]
	s_and_saveexec_b64 s[0:1], s[10:11]
	s_cbranch_execz .LBB0_1282
	v_mov_b32_e32 v99, v177
	s_mov_b32 s24, 0x3e38aa3b
	v_mov_b32_e32 v98, v45
	s_mov_b32 s25, 0x3fb8aa3b
	s_waitcnt lgkmcnt(0)
	v_pk_mul_f32 v[44:45], v[98:99], s[24:25]
	s_nop 0
	v_add_f32_e32 v49, v44, v45
.LBB0_1282:
	s_or_b64 exec, exec, s[0:1]
	v_mov_b32_e32 v44, 0xf149f2ca
	v_mov_b32_e32 v45, 0xf149f2ca
	s_and_saveexec_b64 s[0:1], s[12:13]
	s_cbranch_execz .LBB0_1284
	v_mov_b32_e32 v99, v178
	s_mov_b32 s24, 0x3e38aa3b
	v_mov_b32_e32 v98, v46
	s_mov_b32 s25, 0x3fb8aa3b
	s_waitcnt lgkmcnt(0)
	v_pk_mul_f32 v[98:99], v[98:99], s[24:25]
	s_nop 0
	v_add_f32_e32 v45, v98, v99
.LBB0_1284:
	s_or_b64 exec, exec, s[0:1]
	s_and_saveexec_b64 s[0:1], s[14:15]
	s_cbranch_execz .LBB0_1286
	v_mov_b32_e32 v99, v179
	s_mov_b32 s24, 0x3e38aa3b
	v_mov_b32_e32 v98, v47
	s_mov_b32 s25, 0x3fb8aa3b
	s_waitcnt lgkmcnt(0)
	v_pk_mul_f32 v[46:47], v[98:99], s[24:25]
	s_nop 0
	v_add_f32_e32 v44, v46, v47
.LBB0_1286:
	s_or_b64 exec, exec, s[0:1]
	v_mov_b32_e32 v46, 0xf149f2ca
	v_mov_b32_e32 v47, 0xf149f2ca
	s_and_saveexec_b64 s[0:1], s[16:17]
	s_cbranch_execz .LBB0_1288
	v_mov_b32_e32 v99, v180
	s_mov_b32 s24, 0x3e38aa3b
	v_mov_b32_e32 v98, v40
	s_mov_b32 s25, 0x3fb8aa3b
	s_waitcnt lgkmcnt(0)
	v_pk_mul_f32 v[98:99], v[98:99], s[24:25]
	s_nop 0
	v_add_f32_e32 v47, v98, v99
.LBB0_1288:
	s_or_b64 exec, exec, s[0:1]
	s_and_saveexec_b64 s[0:1], s[18:19]
	s_cbranch_execz .LBB0_1290
	v_mov_b32_e32 v99, v181
	s_mov_b32 s24, 0x3e38aa3b
	v_mov_b32_e32 v98, v41
	s_mov_b32 s25, 0x3fb8aa3b
	s_waitcnt lgkmcnt(0)
	v_pk_mul_f32 v[40:41], v[98:99], s[24:25]
	s_nop 0
	v_add_f32_e32 v46, v40, v41
.LBB0_1290:
	s_or_b64 exec, exec, s[0:1]
	v_mov_b32_e32 v40, 0xf149f2ca
	v_mov_b32_e32 v51, 0xf149f2ca
	s_and_saveexec_b64 s[0:1], s[20:21]
	s_cbranch_execz .LBB0_1292
	v_mov_b32_e32 v99, v182
	s_mov_b32 s24, 0x3e38aa3b
	v_mov_b32_e32 v98, v42
	s_mov_b32 s25, 0x3fb8aa3b
	s_waitcnt lgkmcnt(0)
	v_pk_mul_f32 v[98:99], v[98:99], s[24:25]
	s_nop 0
	v_add_f32_e32 v51, v98, v99
.LBB0_1292:
	s_or_b64 exec, exec, s[0:1]
	s_and_saveexec_b64 s[0:1], s[22:23]
	s_cbranch_execz .LBB0_1294
	v_mov_b32_e32 v41, v183
	s_mov_b32 s24, 0x3e38aa3b
	v_mov_b32_e32 v40, v43
	s_mov_b32 s25, 0x3fb8aa3b
	s_waitcnt lgkmcnt(0)
	v_pk_mul_f32 v[40:41], v[40:41], s[24:25]
	s_nop 0
	v_add_f32_e32 v40, v40, v41
.LBB0_1294:
	s_or_b64 exec, exec, s[0:1]
	v_mov_b32_e32 v41, 0xf149f2ca
	v_mov_b32_e32 v42, 0xf149f2ca
	ds_read_b32 v176, v88 offset:868
	ds_read_b32 v177, v89 offset:868
	ds_read_b32 v178, v90 offset:868
	ds_read_b32 v179, v91 offset:868
	ds_read_b32 v180, v92 offset:868
	ds_read_b32 v181, v94 offset:868
	ds_read_b32 v182, v95 offset:868
	ds_read_b32 v183, v96 offset:868
	s_waitcnt lgkmcnt(0)
	s_and_saveexec_b64 s[0:1], vcc
	s_cbranch_execz .LBB0_1296
	v_mov_b32_e32 v43, v176
	s_mov_b32 s24, 0x3e38aa3b
	v_mov_b32_e32 v42, v36
	s_mov_b32 s25, 0x3fb8aa3b
	s_waitcnt lgkmcnt(0)
	v_pk_mul_f32 v[42:43], v[42:43], s[24:25]
	s_nop 0
	v_add_f32_e32 v42, v42, v43
.LBB0_1296:
	s_or_b64 exec, exec, s[0:1]
	s_and_saveexec_b64 s[0:1], s[10:11]
	s_cbranch_execz .LBB0_1298
	v_mov_b32_e32 v99, v177
	s_mov_b32 s24, 0x3e38aa3b
	v_mov_b32_e32 v98, v37
	s_mov_b32 s25, 0x3fb8aa3b
	s_waitcnt lgkmcnt(0)
	v_pk_mul_f32 v[36:37], v[98:99], s[24:25]
	s_nop 0
	v_add_f32_e32 v41, v36, v37
.LBB0_1298:
	s_or_b64 exec, exec, s[0:1]
	v_mov_b32_e32 v36, 0xf149f2ca
	v_mov_b32_e32 v37, 0xf149f2ca
	s_and_saveexec_b64 s[0:1], s[12:13]
	s_cbranch_execz .LBB0_1300
	v_mov_b32_e32 v99, v178
	s_mov_b32 s24, 0x3e38aa3b
	v_mov_b32_e32 v98, v38
	s_mov_b32 s25, 0x3fb8aa3b
	s_waitcnt lgkmcnt(0)
	v_pk_mul_f32 v[98:99], v[98:99], s[24:25]
	s_nop 0
	v_add_f32_e32 v37, v98, v99
.LBB0_1300:
	s_or_b64 exec, exec, s[0:1]
	s_and_saveexec_b64 s[0:1], s[14:15]
	s_cbranch_execz .LBB0_1302
	v_mov_b32_e32 v99, v179
	s_mov_b32 s24, 0x3e38aa3b
	v_mov_b32_e32 v98, v39
	s_mov_b32 s25, 0x3fb8aa3b
	s_waitcnt lgkmcnt(0)
	v_pk_mul_f32 v[38:39], v[98:99], s[24:25]
	s_nop 0
	v_add_f32_e32 v36, v38, v39
.LBB0_1302:
	s_or_b64 exec, exec, s[0:1]
	v_mov_b32_e32 v38, 0xf149f2ca
	v_mov_b32_e32 v39, 0xf149f2ca
	s_and_saveexec_b64 s[0:1], s[16:17]
	s_cbranch_execz .LBB0_1304
	v_mov_b32_e32 v99, v180
	s_mov_b32 s24, 0x3e38aa3b
	v_mov_b32_e32 v98, v32
	s_mov_b32 s25, 0x3fb8aa3b
	s_waitcnt lgkmcnt(0)
	v_pk_mul_f32 v[98:99], v[98:99], s[24:25]
	s_nop 0
	v_add_f32_e32 v39, v98, v99
.LBB0_1304:
	s_or_b64 exec, exec, s[0:1]
	s_and_saveexec_b64 s[0:1], s[18:19]
	s_cbranch_execz .LBB0_1306
	v_mov_b32_e32 v99, v181
	s_mov_b32 s24, 0x3e38aa3b
	v_mov_b32_e32 v98, v33
	s_mov_b32 s25, 0x3fb8aa3b
	s_waitcnt lgkmcnt(0)
	v_pk_mul_f32 v[32:33], v[98:99], s[24:25]
	s_nop 0
	v_add_f32_e32 v38, v32, v33
.LBB0_1306:
	s_or_b64 exec, exec, s[0:1]
	v_mov_b32_e32 v32, 0xf149f2ca
	v_mov_b32_e32 v43, 0xf149f2ca
	s_and_saveexec_b64 s[0:1], s[20:21]
	s_cbranch_execz .LBB0_1308
	v_mov_b32_e32 v99, v182
	s_mov_b32 s24, 0x3e38aa3b
	v_mov_b32_e32 v98, v34
	s_mov_b32 s25, 0x3fb8aa3b
	s_waitcnt lgkmcnt(0)
	v_pk_mul_f32 v[98:99], v[98:99], s[24:25]
	s_nop 0
	v_add_f32_e32 v43, v98, v99
.LBB0_1308:
	s_or_b64 exec, exec, s[0:1]
	s_and_saveexec_b64 s[0:1], s[22:23]
	s_cbranch_execz .LBB0_1310
	v_mov_b32_e32 v33, v183
	s_mov_b32 s24, 0x3e38aa3b
	v_mov_b32_e32 v32, v35
	s_mov_b32 s25, 0x3fb8aa3b
	s_waitcnt lgkmcnt(0)
	v_pk_mul_f32 v[32:33], v[32:33], s[24:25]
	s_nop 0
	v_add_f32_e32 v32, v32, v33
.LBB0_1310:
	s_or_b64 exec, exec, s[0:1]
	v_mov_b32_e32 v33, 0xf149f2ca
	v_mov_b32_e32 v34, 0xf149f2ca
	ds_read_b32 v176, v88 offset:992
	ds_read_b32 v177, v89 offset:992
	ds_read_b32 v178, v90 offset:992
	ds_read_b32 v179, v91 offset:992
	ds_read_b32 v180, v92 offset:992
	ds_read_b32 v181, v94 offset:992
	ds_read_b32 v182, v95 offset:992
	ds_read_b32 v183, v96 offset:992
	s_waitcnt lgkmcnt(0)
	s_and_saveexec_b64 s[0:1], vcc
	s_cbranch_execz .LBB0_1312
	v_mov_b32_e32 v35, v176
	s_mov_b32 s24, 0x3e38aa3b
	v_mov_b32_e32 v34, v28
	s_mov_b32 s25, 0x3fb8aa3b
	s_waitcnt lgkmcnt(0)
	v_pk_mul_f32 v[34:35], v[34:35], s[24:25]
	s_nop 0
	v_add_f32_e32 v34, v34, v35
.LBB0_1312:
	s_or_b64 exec, exec, s[0:1]
	s_and_saveexec_b64 s[0:1], s[10:11]
	s_cbranch_execz .LBB0_1314
	v_mov_b32_e32 v99, v177
	s_mov_b32 s24, 0x3e38aa3b
	v_mov_b32_e32 v98, v29
	s_mov_b32 s25, 0x3fb8aa3b
	s_waitcnt lgkmcnt(0)
	v_pk_mul_f32 v[28:29], v[98:99], s[24:25]
	s_nop 0
	v_add_f32_e32 v33, v28, v29
.LBB0_1314:
	s_or_b64 exec, exec, s[0:1]
	v_mov_b32_e32 v28, 0xf149f2ca
	v_mov_b32_e32 v29, 0xf149f2ca
	s_and_saveexec_b64 s[0:1], s[12:13]
	s_cbranch_execz .LBB0_1316
	v_mov_b32_e32 v99, v178
	s_mov_b32 s24, 0x3e38aa3b
	v_mov_b32_e32 v98, v30
	s_mov_b32 s25, 0x3fb8aa3b
	s_waitcnt lgkmcnt(0)
	v_pk_mul_f32 v[98:99], v[98:99], s[24:25]
	s_nop 0
	v_add_f32_e32 v29, v98, v99
.LBB0_1316:
	s_or_b64 exec, exec, s[0:1]
	s_and_saveexec_b64 s[0:1], s[14:15]
	s_cbranch_execz .LBB0_1318
	v_mov_b32_e32 v99, v179
	s_mov_b32 s24, 0x3e38aa3b
	v_mov_b32_e32 v98, v31
	s_mov_b32 s25, 0x3fb8aa3b
	s_waitcnt lgkmcnt(0)
	v_pk_mul_f32 v[30:31], v[98:99], s[24:25]
	s_nop 0
	v_add_f32_e32 v28, v30, v31
.LBB0_1318:
	s_or_b64 exec, exec, s[0:1]
	v_mov_b32_e32 v30, 0xf149f2ca
	v_mov_b32_e32 v31, 0xf149f2ca
	s_and_saveexec_b64 s[0:1], s[16:17]
	s_cbranch_execz .LBB0_1320
	v_mov_b32_e32 v99, v180
	s_mov_b32 s24, 0x3e38aa3b
	v_mov_b32_e32 v98, v24
	s_mov_b32 s25, 0x3fb8aa3b
	s_waitcnt lgkmcnt(0)
	v_pk_mul_f32 v[98:99], v[98:99], s[24:25]
	s_nop 0
	v_add_f32_e32 v31, v98, v99
.LBB0_1320:
	s_or_b64 exec, exec, s[0:1]
	s_and_saveexec_b64 s[0:1], s[18:19]
	s_cbranch_execz .LBB0_1322
	v_mov_b32_e32 v99, v181
	s_mov_b32 s24, 0x3e38aa3b
	v_mov_b32_e32 v98, v25
	s_mov_b32 s25, 0x3fb8aa3b
	s_waitcnt lgkmcnt(0)
	v_pk_mul_f32 v[24:25], v[98:99], s[24:25]
	s_nop 0
	v_add_f32_e32 v30, v24, v25
.LBB0_1322:
	s_or_b64 exec, exec, s[0:1]
	v_mov_b32_e32 v24, 0xf149f2ca
	v_mov_b32_e32 v35, 0xf149f2ca
	s_and_saveexec_b64 s[0:1], s[20:21]
	s_cbranch_execz .LBB0_1324
	v_mov_b32_e32 v99, v182
	s_mov_b32 s24, 0x3e38aa3b
	v_mov_b32_e32 v98, v26
	s_mov_b32 s25, 0x3fb8aa3b
	s_waitcnt lgkmcnt(0)
	v_pk_mul_f32 v[98:99], v[98:99], s[24:25]
	s_nop 0
	v_add_f32_e32 v35, v98, v99
.LBB0_1324:
	s_or_b64 exec, exec, s[0:1]
	s_and_saveexec_b64 s[0:1], s[22:23]
	s_cbranch_execz .LBB0_1326
	v_mov_b32_e32 v25, v183
	s_mov_b32 s24, 0x3e38aa3b
	v_mov_b32_e32 v24, v27
	s_mov_b32 s25, 0x3fb8aa3b
	s_waitcnt lgkmcnt(0)
	v_pk_mul_f32 v[24:25], v[24:25], s[24:25]
	s_nop 0
	v_add_f32_e32 v24, v24, v25
.LBB0_1326:
	s_or_b64 exec, exec, s[0:1]
	v_mov_b32_e32 v25, 0xf149f2ca
	v_mov_b32_e32 v26, 0xf149f2ca
	ds_read_b32 v176, v88 offset:1116
	ds_read_b32 v177, v89 offset:1116
	ds_read_b32 v178, v90 offset:1116
	ds_read_b32 v179, v91 offset:1116
	ds_read_b32 v180, v92 offset:1116
	ds_read_b32 v181, v94 offset:1116
	ds_read_b32 v182, v95 offset:1116
	ds_read_b32 v183, v96 offset:1116
	s_waitcnt lgkmcnt(0)
	s_and_saveexec_b64 s[0:1], vcc
	s_cbranch_execz .LBB0_1328
	v_mov_b32_e32 v27, v176
	s_mov_b32 s24, 0x3e38aa3b
	v_mov_b32_e32 v26, v20
	s_mov_b32 s25, 0x3fb8aa3b
	s_waitcnt lgkmcnt(0)
	v_pk_mul_f32 v[26:27], v[26:27], s[24:25]
	s_nop 0
	v_add_f32_e32 v26, v26, v27
.LBB0_1328:
	s_or_b64 exec, exec, s[0:1]
	s_and_saveexec_b64 s[0:1], s[10:11]
	s_cbranch_execz .LBB0_1330
	v_mov_b32_e32 v99, v177
	s_mov_b32 s24, 0x3e38aa3b
	v_mov_b32_e32 v98, v21
	s_mov_b32 s25, 0x3fb8aa3b
	s_waitcnt lgkmcnt(0)
	v_pk_mul_f32 v[20:21], v[98:99], s[24:25]
	s_nop 0
	v_add_f32_e32 v25, v20, v21
.LBB0_1330:
	s_or_b64 exec, exec, s[0:1]
	v_mov_b32_e32 v20, 0xf149f2ca
	v_mov_b32_e32 v21, 0xf149f2ca
	s_and_saveexec_b64 s[0:1], s[12:13]
	s_cbranch_execz .LBB0_1332
	v_mov_b32_e32 v99, v178
	s_mov_b32 s24, 0x3e38aa3b
	v_mov_b32_e32 v98, v22
	s_mov_b32 s25, 0x3fb8aa3b
	s_waitcnt lgkmcnt(0)
	v_pk_mul_f32 v[98:99], v[98:99], s[24:25]
	s_nop 0
	v_add_f32_e32 v21, v98, v99
.LBB0_1332:
	s_or_b64 exec, exec, s[0:1]
	s_and_saveexec_b64 s[0:1], s[14:15]
	s_cbranch_execz .LBB0_1334
	v_mov_b32_e32 v99, v179
	s_mov_b32 s24, 0x3e38aa3b
	v_mov_b32_e32 v98, v23
	s_mov_b32 s25, 0x3fb8aa3b
	s_waitcnt lgkmcnt(0)
	v_pk_mul_f32 v[22:23], v[98:99], s[24:25]
	s_nop 0
	v_add_f32_e32 v20, v22, v23
.LBB0_1334:
	s_or_b64 exec, exec, s[0:1]
	v_mov_b32_e32 v22, 0xf149f2ca
	v_mov_b32_e32 v23, 0xf149f2ca
	s_and_saveexec_b64 s[0:1], s[16:17]
	s_cbranch_execz .LBB0_1336
	v_mov_b32_e32 v99, v180
	s_mov_b32 s24, 0x3e38aa3b
	v_mov_b32_e32 v98, v16
	s_mov_b32 s25, 0x3fb8aa3b
	s_waitcnt lgkmcnt(0)
	v_pk_mul_f32 v[98:99], v[98:99], s[24:25]
	s_nop 0
	v_add_f32_e32 v23, v98, v99
.LBB0_1336:
	s_or_b64 exec, exec, s[0:1]
	s_and_saveexec_b64 s[0:1], s[18:19]
	s_cbranch_execz .LBB0_1338
	v_mov_b32_e32 v99, v181
	s_mov_b32 s24, 0x3e38aa3b
	v_mov_b32_e32 v98, v17
	s_mov_b32 s25, 0x3fb8aa3b
	s_waitcnt lgkmcnt(0)
	v_pk_mul_f32 v[16:17], v[98:99], s[24:25]
	s_nop 0
	v_add_f32_e32 v22, v16, v17
.LBB0_1338:
	s_or_b64 exec, exec, s[0:1]
	v_mov_b32_e32 v17, 0xf149f2ca
	v_mov_b32_e32 v27, 0xf149f2ca
	s_and_saveexec_b64 s[0:1], s[20:21]
	s_cbranch_execz .LBB0_1340
	v_mov_b32_e32 v99, v182
	s_mov_b32 s24, 0x3e38aa3b
	v_mov_b32_e32 v98, v18
	s_mov_b32 s25, 0x3fb8aa3b
	s_waitcnt lgkmcnt(0)
	v_pk_mul_f32 v[98:99], v[98:99], s[24:25]
	s_nop 0
	v_add_f32_e32 v27, v98, v99
.LBB0_1340:
	s_or_b64 exec, exec, s[0:1]
	s_and_saveexec_b64 s[0:1], s[22:23]
	s_cbranch_execz .LBB0_1342
	v_mov_b32_e32 v17, v183
	s_mov_b32 s24, 0x3e38aa3b
	v_mov_b32_e32 v16, v19
	s_mov_b32 s25, 0x3fb8aa3b
	s_waitcnt lgkmcnt(0)
	v_pk_mul_f32 v[16:17], v[16:17], s[24:25]
	s_nop 0
	v_add_f32_e32 v17, v16, v17
.LBB0_1342:
	s_or_b64 exec, exec, s[0:1]
	v_mov_b32_e32 v16, 0xf149f2ca
	v_mov_b32_e32 v18, 0xf149f2ca
	ds_read_b32 v176, v88 offset:1240
	ds_read_b32 v177, v89 offset:1240
	ds_read_b32 v178, v90 offset:1240
	ds_read_b32 v179, v91 offset:1240
	ds_read_b32 v180, v92 offset:1240
	ds_read_b32 v181, v94 offset:1240
	ds_read_b32 v182, v95 offset:1240
	ds_read_b32 v183, v96 offset:1240
	s_waitcnt lgkmcnt(0)
	s_and_saveexec_b64 s[0:1], vcc
	s_cbranch_execz .LBB0_1344
	v_mov_b32_e32 v19, v176
	s_mov_b32 s24, 0x3e38aa3b
	v_mov_b32_e32 v18, v12
	s_mov_b32 s25, 0x3fb8aa3b
	s_waitcnt lgkmcnt(0)
	v_pk_mul_f32 v[18:19], v[18:19], s[24:25]
	s_nop 0
	v_add_f32_e32 v18, v18, v19
.LBB0_1344:
	s_or_b64 exec, exec, s[0:1]
	s_and_saveexec_b64 s[0:1], s[10:11]
	s_cbranch_execz .LBB0_1346
	v_mov_b32_e32 v89, v177
	s_mov_b32 s10, 0x3e38aa3b
	v_mov_b32_e32 v88, v13
	s_mov_b32 s11, 0x3fb8aa3b
	s_waitcnt lgkmcnt(0)
	v_pk_mul_f32 v[12:13], v[88:89], s[10:11]
	s_nop 0
	v_add_f32_e32 v16, v12, v13
.LBB0_1346:
	s_or_b64 exec, exec, s[0:1]
	v_mov_b32_e32 v12, 0xf149f2ca
	v_mov_b32_e32 v13, 0xf149f2ca
	s_and_saveexec_b64 s[0:1], s[12:13]
	s_cbranch_execz .LBB0_1348
	v_mov_b32_e32 v89, v178
	s_mov_b32 s10, 0x3e38aa3b
	v_mov_b32_e32 v88, v14
	s_mov_b32 s11, 0x3fb8aa3b
	s_waitcnt lgkmcnt(0)
	v_pk_mul_f32 v[88:89], v[88:89], s[10:11]
	s_nop 0
	v_add_f32_e32 v13, v88, v89
.LBB0_1348:
	s_or_b64 exec, exec, s[0:1]
	s_and_saveexec_b64 s[0:1], s[14:15]
	s_cbranch_execz .LBB0_1350
	v_mov_b32_e32 v89, v179
	s_mov_b32 s10, 0x3e38aa3b
	v_mov_b32_e32 v88, v15
	s_mov_b32 s11, 0x3fb8aa3b
	s_waitcnt lgkmcnt(0)
	v_pk_mul_f32 v[14:15], v[88:89], s[10:11]
	s_nop 0
	v_add_f32_e32 v12, v14, v15
.LBB0_1350:
	s_or_b64 exec, exec, s[0:1]
	v_mov_b32_e32 v14, 0xf149f2ca
	v_mov_b32_e32 v15, 0xf149f2ca
	s_and_saveexec_b64 s[0:1], s[16:17]
	s_cbranch_execz .LBB0_1352
	v_mov_b32_e32 v89, v180
	s_mov_b32 s10, 0x3e38aa3b
	v_mov_b32_e32 v88, v8
	s_mov_b32 s11, 0x3fb8aa3b
	s_waitcnt lgkmcnt(0)
	v_pk_mul_f32 v[88:89], v[88:89], s[10:11]
	s_nop 0
	v_add_f32_e32 v15, v88, v89
.LBB0_1352:
	s_or_b64 exec, exec, s[0:1]
	s_and_saveexec_b64 s[0:1], s[18:19]
	s_cbranch_execz .LBB0_1354
	v_mov_b32_e32 v89, v181
	s_mov_b32 s10, 0x3e38aa3b
	v_mov_b32_e32 v88, v9
	s_mov_b32 s11, 0x3fb8aa3b
	s_waitcnt lgkmcnt(0)
	v_pk_mul_f32 v[8:9], v[88:89], s[10:11]
	s_nop 0
	v_add_f32_e32 v14, v8, v9
.LBB0_1354:
	s_or_b64 exec, exec, s[0:1]
	v_mov_b32_e32 v19, 0xf149f2ca
	v_mov_b32_e32 v91, 0xf149f2ca
	s_and_saveexec_b64 s[0:1], s[20:21]
	s_cbranch_execz .LBB0_1356
	v_mov_b32_e32 v9, v182
	s_mov_b32 s10, 0x3e38aa3b
	v_mov_b32_e32 v8, v10
	s_mov_b32 s11, 0x3fb8aa3b
	s_waitcnt lgkmcnt(0)
	v_pk_mul_f32 v[8:9], v[8:9], s[10:11]
	s_nop 0
	v_add_f32_e32 v91, v8, v9
.LBB0_1356:
	s_or_b64 exec, exec, s[0:1]
	s_and_saveexec_b64 s[0:1], s[22:23]
	s_cbranch_execz .LBB0_1358
	v_mov_b32_e32 v9, v183
	s_mov_b32 s10, 0x3e38aa3b
	v_mov_b32_e32 v8, v11
	s_mov_b32 s11, 0x3fb8aa3b
	s_waitcnt lgkmcnt(0)
	v_pk_mul_f32 v[8:9], v[8:9], s[10:11]
	s_nop 0
	v_add_f32_e32 v19, v8, v9
